# LN (post-mixer) row loop: next row's loads prefetched one iteration ahead; carry-in pads in residual epilogue glue
# speedup vs baseline: 1.5167x; 1.0051x over previous
.Lg4_r1_nl:
	s_waitcnt lgkmcnt(1)
	v_mfma_f32_16x16x32_f16 v[0:3], v[132:135], v[242:245], v[0:3]
	v_mfma_f32_16x16x32_f16 v[16:19], v[136:139], v[242:245], v[16:19]
	v_mfma_f32_16x16x32_f16 v[32:35], v[140:143], v[242:245], v[32:35]
	v_mfma_f32_16x16x32_f16 v[48:51], v[144:147], v[242:245], v[48:51]
	v_mfma_f32_16x16x32_f16 v[64:67], v[148:151], v[242:245], v[64:67]
	v_mfma_f32_16x16x32_f16 v[80:83], v[152:155], v[242:245], v[80:83]
	v_mfma_f32_16x16x32_f16 v[96:99], v[156:159], v[242:245], v[96:99]
	v_mfma_f32_16x16x32_f16 v[116:119], v[160:163], v[242:245], v[116:119]
	ds_read_b128 v[242:245], v223 offset:36864
	s_waitcnt lgkmcnt(1)
	v_mfma_f32_16x16x32_f16 v[4:7], v[132:135], v[112:115], v[4:7]
	v_mfma_f32_16x16x32_f16 v[20:23], v[136:139], v[112:115], v[20:23]
	v_mfma_f32_16x16x32_f16 v[36:39], v[140:143], v[112:115], v[36:39]
	v_mfma_f32_16x16x32_f16 v[52:55], v[144:147], v[112:115], v[52:55]
	v_mfma_f32_16x16x32_f16 v[68:71], v[148:151], v[112:115], v[68:71]
	v_mfma_f32_16x16x32_f16 v[84:87], v[152:155], v[112:115], v[84:87]
	v_mfma_f32_16x16x32_f16 v[100:103], v[156:159], v[112:115], v[100:103]
	v_mfma_f32_16x16x32_f16 v[120:123], v[160:163], v[112:115], v[120:123]
	ds_read_b128 v[112:115], v223 offset:38912
	s_waitcnt lgkmcnt(1)
	v_mfma_f32_16x16x32_f16 v[8:11], v[132:135], v[242:245], v[8:11]
	v_mfma_f32_16x16x32_f16 v[24:27], v[136:139], v[242:245], v[24:27]
	v_mfma_f32_16x16x32_f16 v[40:43], v[140:143], v[242:245], v[40:43]
	v_mfma_f32_16x16x32_f16 v[56:59], v[144:147], v[242:245], v[56:59]
	v_mfma_f32_16x16x32_f16 v[72:75], v[148:151], v[242:245], v[72:75]
	v_mfma_f32_16x16x32_f16 v[88:91], v[152:155], v[242:245], v[88:91]
	v_mfma_f32_16x16x32_f16 v[104:107], v[156:159], v[242:245], v[104:107]
	v_mfma_f32_16x16x32_f16 v[124:127], v[160:163], v[242:245], v[124:127]
	ds_read_b128 v[242:245], v233 offset:32768
	s_waitcnt lgkmcnt(1)
	v_mfma_f32_16x16x32_f16 v[12:15], v[132:135], v[112:115], v[12:15]
	v_mfma_f32_16x16x32_f16 v[28:31], v[136:139], v[112:115], v[28:31]
	v_mfma_f32_16x16x32_f16 v[44:47], v[140:143], v[112:115], v[44:47]
	v_mfma_f32_16x16x32_f16 v[60:63], v[144:147], v[112:115], v[60:63]
	v_mfma_f32_16x16x32_f16 v[76:79], v[148:151], v[112:115], v[76:79]
	v_mfma_f32_16x16x32_f16 v[92:95], v[152:155], v[112:115], v[92:95]
	v_mfma_f32_16x16x32_f16 v[108:111], v[156:159], v[112:115], v[108:111]
	v_mfma_f32_16x16x32_f16 v[128:131], v[160:163], v[112:115], v[128:131]
	ds_read_b128 v[112:115], v233 offset:34816
	s_waitcnt lgkmcnt(1)
	v_mfma_f32_16x16x32_f16 v[0:3], v[164:167], v[242:245], v[0:3]
	v_mfma_f32_16x16x32_f16 v[16:19], v[168:171], v[242:245], v[16:19]
	v_mfma_f32_16x16x32_f16 v[32:35], v[172:175], v[242:245], v[32:35]
	v_mfma_f32_16x16x32_f16 v[48:51], v[176:179], v[242:245], v[48:51]
	v_mfma_f32_16x16x32_f16 v[64:67], v[224:227], v[242:245], v[64:67]
	v_mfma_f32_16x16x32_f16 v[80:83], v[228:231], v[242:245], v[80:83]
	v_mfma_f32_16x16x32_f16 v[96:99], v[234:237], v[242:245], v[96:99]
	v_mfma_f32_16x16x32_f16 v[116:119], v[238:241], v[242:245], v[116:119]
	ds_read_b128 v[242:245], v233 offset:36864
	s_waitcnt lgkmcnt(1)
	v_mfma_f32_16x16x32_f16 v[4:7], v[164:167], v[112:115], v[4:7]
	v_mfma_f32_16x16x32_f16 v[20:23], v[168:171], v[112:115], v[20:23]
	v_mfma_f32_16x16x32_f16 v[36:39], v[172:175], v[112:115], v[36:39]
	v_mfma_f32_16x16x32_f16 v[52:55], v[176:179], v[112:115], v[52:55]
	v_mfma_f32_16x16x32_f16 v[68:71], v[224:227], v[112:115], v[68:71]
	v_mfma_f32_16x16x32_f16 v[84:87], v[228:231], v[112:115], v[84:87]
	v_mfma_f32_16x16x32_f16 v[100:103], v[234:237], v[112:115], v[100:103]
	v_mfma_f32_16x16x32_f16 v[120:123], v[238:241], v[112:115], v[120:123]
	ds_read_b128 v[112:115], v233 offset:38912
	s_waitcnt lgkmcnt(1)
	v_mfma_f32_16x16x32_f16 v[8:11], v[164:167], v[242:245], v[8:11]
	v_mfma_f32_16x16x32_f16 v[24:27], v[168:171], v[242:245], v[24:27]
	v_mfma_f32_16x16x32_f16 v[40:43], v[172:175], v[242:245], v[40:43]
	v_mfma_f32_16x16x32_f16 v[56:59], v[176:179], v[242:245], v[56:59]
	v_mfma_f32_16x16x32_f16 v[72:75], v[224:227], v[242:245], v[72:75]
	v_mfma_f32_16x16x32_f16 v[88:91], v[228:231], v[242:245], v[88:91]
	v_mfma_f32_16x16x32_f16 v[104:107], v[234:237], v[242:245], v[104:107]
	v_mfma_f32_16x16x32_f16 v[124:127], v[238:241], v[242:245], v[124:127]
	s_waitcnt lgkmcnt(0)
	v_mfma_f32_16x16x32_f16 v[12:15], v[164:167], v[112:115], v[12:15]
	v_mfma_f32_16x16x32_f16 v[28:31], v[168:171], v[112:115], v[28:31]
	v_mfma_f32_16x16x32_f16 v[44:47], v[172:175], v[112:115], v[44:47]
	v_mfma_f32_16x16x32_f16 v[60:63], v[176:179], v[112:115], v[60:63]
	v_mfma_f32_16x16x32_f16 v[76:79], v[224:227], v[112:115], v[76:79]
	v_mfma_f32_16x16x32_f16 v[92:95], v[228:231], v[112:115], v[92:95]
	v_mfma_f32_16x16x32_f16 v[108:111], v[234:237], v[112:115], v[108:111]
	v_mfma_f32_16x16x32_f16 v[128:131], v[238:241], v[112:115], v[128:131]
	v_xor_b32_e32 v223, 0x4000, v223
	v_xor_b32_e32 v233, 0x4000, v233
	s_sub_u32 s16, s16, 1
	s_cmp_lg_u32 s16, -1
	s_cbranch_scc1 .Lg4_r1
	s_nop 7
	v_bfe_u32 v208, v182, 7, 1
	v_bfe_u32 v223, v182, 4, 2
	v_lshlrev_b32_e32 v223, 2, v223
	v_lshl_or_b32 v208, v208, 7, v223
	v_add_u32_e32 v180, s0, v208
	v_bfe_u32 v208, v182, 6, 1
	v_and_b32_e32 v223, 15, v182
	v_lshl_or_b32 v208, v208, 6, v223
	v_add_u32_e32 v208, s14, v208
	v_lshlrev_b32_e32 v181, 2, v208
	s_lshr_b32 s4, s0, 13
	s_add_i32 s4, s4, s12
	s_mul_hi_i32 s9, s4, 0x9000
	s_mul_i32 s8, s4, 0x9000
	s_add_u32 s8, s50, s8
	s_addc_u32 s9, s51, s9
	s_add_u32 s8, s8, s48
	s_addc_u32 s9, s9, 0
	v_mov_b32_e32 v247, s9
	v_add_co_u32_e32 v246, vcc, s8, v181
	s_nop 1
	v_addc_co_u32_e32 v247, vcc, 0, v247, vcc
	v_lshl_add_u32 v164, v180, 12, v181
	v_add_u32_e32 v165, 0x1000, v164
	v_add_u32_e32 v166, 0x3000, v164
	v_add_u32_e32 v167, 0x11000, v164
	v_add_u32_e32 v168, 0x13000, v164
	v_add_u32_e32 v169, 0x21000, v164
	v_add_u32_e32 v170, 0x23000, v164
	v_add_u32_e32 v171, 0x31000, v164
	v_add_u32_e32 v172, 0x33000, v164
	v_lshlrev_b32_e32 v115, 3, v180
	v_add_u32_e32 v115, 0x1e200000, v115
	v_add_u32_e32 v208, 0x2000, v181
	v_mov_b32_e32 v223, s71
	v_cmp_ne_u32_e64 s[98:99], 0, v223
	global_load_dwordx2 v[132:133], v115, s[30:31] offset:0
	global_load_dwordx2 v[134:135], v115, s[30:31] offset:8
	global_load_dwordx2 v[136:137], v115, s[30:31] offset:16
	global_load_dwordx2 v[138:139], v115, s[30:31] offset:24
	global_load_dwordx2 v[140:141], v115, s[30:31] offset:128
	global_load_dwordx2 v[142:143], v115, s[30:31] offset:136
	global_load_dwordx2 v[144:145], v115, s[30:31] offset:144
	global_load_dwordx2 v[146:147], v115, s[30:31] offset:152
	global_load_dwordx2 v[148:149], v115, s[30:31] offset:256
	global_load_dwordx2 v[150:151], v115, s[30:31] offset:264
	global_load_dwordx2 v[152:153], v115, s[30:31] offset:272
	global_load_dwordx2 v[154:155], v115, s[30:31] offset:280
	global_load_dwordx2 v[156:157], v115, s[30:31] offset:384
	global_load_dwordx2 v[158:159], v115, s[30:31] offset:392
	global_load_dwordx2 v[160:161], v115, s[30:31] offset:400
	global_load_dwordx2 v[162:163], v115, s[30:31] offset:408
	global_load_dword v239, v208, s[24:25] offset:0
	global_load_dword v243, v208, s[26:27] offset:0
	global_load_dword v240, v208, s[24:25] offset:64
	global_load_dword v244, v208, s[26:27] offset:64
	global_load_dword v241, v208, s[24:25] offset:128
	global_load_dword v245, v208, s[26:27] offset:128
	global_load_dword v242, v208, s[24:25] offset:192
	global_load_dword v112, v208, s[26:27] offset:192
	global_load_dword v173, v[246:247], off offset:0
	global_load_dword v174, v[246:247], off offset:64
	global_load_dword v175, v[246:247], off offset:128
	global_load_dword v176, v[246:247], off offset:192
	global_load_dword v177, v165, s[2:3] offset:-4096
	global_load_dword v178, v165, s[2:3] offset:0
	global_load_dword v179, v166, s[2:3] offset:-4096
	global_load_dword v224, v166, s[2:3] offset:0
	global_load_dword v225, v167, s[2:3] offset:-4096
	global_load_dword v226, v167, s[2:3] offset:0
	global_load_dword v227, v168, s[2:3] offset:-4096
	global_load_dword v228, v168, s[2:3] offset:0
	global_load_dword v229, v169, s[2:3] offset:-4096
	global_load_dword v230, v169, s[2:3] offset:0
	global_load_dword v231, v170, s[2:3] offset:-4096
	global_load_dword v234, v170, s[2:3] offset:0
	global_load_dword v235, v171, s[2:3] offset:-4096
	global_load_dword v236, v171, s[2:3] offset:0
	global_load_dword v237, v172, s[2:3] offset:-4096
	global_load_dword v238, v172, s[2:3] offset:0
	s_waitcnt vmcnt(15)
	v_add_f32_e32 v173, 1.0, v173
	v_add_f32_e32 v174, 1.0, v174
	v_add_f32_e32 v175, 1.0, v175
	v_add_f32_e32 v176, 1.0, v176
	v_mul_f32_e32 v173, 0.5, v173
	v_mul_f32_e32 v174, 0.5, v174
	v_mul_f32_e32 v175, 0.5, v175
	v_mul_f32_e32 v176, 0.5, v176
	v_sub_f32_e32 v233, v177, v132
	v_mul_f32_e32 v233, v233, v133
	v_fma_f32 v233, v239, v233, v243
	v_cndmask_b32_e64 v177, v177, v233, s[98:99]
	v_mul_f32_e32 v0, v0, v173
	v_fmac_f32_e32 v0, 0x3fb504f3, v177
	global_load_dword v177, v165, s[2:3] offset:-4032
	global_store_dword v165, v0, s[28:29] offset:-4096
	s_waitcnt vmcnt(16)
	v_sub_f32_e32 v233, v178, v134
	v_mul_f32_e32 v233, v233, v135
	v_fma_f32 v233, v239, v233, v243
	v_cndmask_b32_e64 v178, v178, v233, s[98:99]
	v_mul_f32_e32 v1, v1, v173
	v_fmac_f32_e32 v1, 0x3fb504f3, v178
	global_load_dword v178, v165, s[2:3] offset:64
	global_store_dword v165, v1, s[28:29] offset:0
	s_waitcnt vmcnt(17)
	v_sub_f32_e32 v233, v179, v136
	v_mul_f32_e32 v233, v233, v137
	v_fma_f32 v233, v239, v233, v243
	v_cndmask_b32_e64 v179, v179, v233, s[98:99]
	v_mul_f32_e32 v2, v2, v173
	v_fmac_f32_e32 v2, 0x3fb504f3, v179
	global_load_dword v179, v166, s[2:3] offset:-4032
	global_store_dword v166, v2, s[28:29] offset:-4096
	s_waitcnt vmcnt(18)
	v_sub_f32_e32 v233, v224, v138
	v_mul_f32_e32 v233, v233, v139
	v_fma_f32 v233, v239, v233, v243
	v_cndmask_b32_e64 v224, v224, v233, s[98:99]
	v_mul_f32_e32 v3, v3, v173
	v_fmac_f32_e32 v3, 0x3fb504f3, v224
	global_load_dword v224, v166, s[2:3] offset:64
	global_store_dword v166, v3, s[28:29] offset:0
	s_waitcnt vmcnt(19)
	v_sub_f32_e32 v233, v225, v140
	v_mul_f32_e32 v233, v233, v141
	v_fma_f32 v233, v239, v233, v243
	v_cndmask_b32_e64 v225, v225, v233, s[98:99]
	v_mul_f32_e32 v16, v16, v173
	v_fmac_f32_e32 v16, 0x3fb504f3, v225
	global_load_dword v225, v167, s[2:3] offset:-4032
	global_store_dword v167, v16, s[28:29] offset:-4096
	s_waitcnt vmcnt(20)
	v_sub_f32_e32 v233, v226, v142
	v_mul_f32_e32 v233, v233, v143
	v_fma_f32 v233, v239, v233, v243
	v_cndmask_b32_e64 v226, v226, v233, s[98:99]
	v_mul_f32_e32 v17, v17, v173
	v_fmac_f32_e32 v17, 0x3fb504f3, v226
	global_load_dword v226, v167, s[2:3] offset:64
	global_store_dword v167, v17, s[28:29] offset:0
	s_waitcnt vmcnt(21)
	v_sub_f32_e32 v233, v227, v144
	v_mul_f32_e32 v233, v233, v145
	v_fma_f32 v233, v239, v233, v243
	v_cndmask_b32_e64 v227, v227, v233, s[98:99]
	v_mul_f32_e32 v18, v18, v173
	v_fmac_f32_e32 v18, 0x3fb504f3, v227
	global_load_dword v227, v168, s[2:3] offset:-4032
	global_store_dword v168, v18, s[28:29] offset:-4096
	s_waitcnt vmcnt(22)
	v_sub_f32_e32 v233, v228, v146
	v_mul_f32_e32 v233, v233, v147
	v_fma_f32 v233, v239, v233, v243
	v_cndmask_b32_e64 v228, v228, v233, s[98:99]
	v_mul_f32_e32 v19, v19, v173
	v_fmac_f32_e32 v19, 0x3fb504f3, v228
	global_load_dword v228, v168, s[2:3] offset:64
	global_store_dword v168, v19, s[28:29] offset:0
	s_waitcnt vmcnt(23)
	v_sub_f32_e32 v233, v229, v148
	v_mul_f32_e32 v233, v233, v149
	v_fma_f32 v233, v239, v233, v243
	v_cndmask_b32_e64 v229, v229, v233, s[98:99]
	v_mul_f32_e32 v32, v32, v173
	v_fmac_f32_e32 v32, 0x3fb504f3, v229
	global_load_dword v229, v169, s[2:3] offset:-4032
	global_store_dword v169, v32, s[28:29] offset:-4096
	s_waitcnt vmcnt(24)
	v_sub_f32_e32 v233, v230, v150
	v_mul_f32_e32 v233, v233, v151
	v_fma_f32 v233, v239, v233, v243
	v_cndmask_b32_e64 v230, v230, v233, s[98:99]
	v_mul_f32_e32 v33, v33, v173
	v_fmac_f32_e32 v33, 0x3fb504f3, v230
	global_load_dword v230, v169, s[2:3] offset:64
	global_store_dword v169, v33, s[28:29] offset:0
	s_waitcnt vmcnt(25)
	v_sub_f32_e32 v233, v231, v152
	v_mul_f32_e32 v233, v233, v153
	v_fma_f32 v233, v239, v233, v243
	v_cndmask_b32_e64 v231, v231, v233, s[98:99]
	v_mul_f32_e32 v34, v34, v173
	v_fmac_f32_e32 v34, 0x3fb504f3, v231
	global_load_dword v231, v170, s[2:3] offset:-4032
	global_store_dword v170, v34, s[28:29] offset:-4096
	s_waitcnt vmcnt(26)
	v_sub_f32_e32 v233, v234, v154
	v_mul_f32_e32 v233, v233, v155
	v_fma_f32 v233, v239, v233, v243
	v_cndmask_b32_e64 v234, v234, v233, s[98:99]
	v_mul_f32_e32 v35, v35, v173
	v_fmac_f32_e32 v35, 0x3fb504f3, v234
	global_load_dword v234, v170, s[2:3] offset:64
	global_store_dword v170, v35, s[28:29] offset:0
	s_waitcnt vmcnt(27)
	v_sub_f32_e32 v233, v235, v156
	v_mul_f32_e32 v233, v233, v157
	v_fma_f32 v233, v239, v233, v243
	v_cndmask_b32_e64 v235, v235, v233, s[98:99]
	v_mul_f32_e32 v48, v48, v173
	v_fmac_f32_e32 v48, 0x3fb504f3, v235
	global_load_dword v235, v171, s[2:3] offset:-4032
	global_store_dword v171, v48, s[28:29] offset:-4096
	s_waitcnt vmcnt(28)
	v_sub_f32_e32 v233, v236, v158
	v_mul_f32_e32 v233, v233, v159
	v_fma_f32 v233, v239, v233, v243
	v_cndmask_b32_e64 v236, v236, v233, s[98:99]
	v_mul_f32_e32 v49, v49, v173
	v_fmac_f32_e32 v49, 0x3fb504f3, v236
	global_load_dword v236, v171, s[2:3] offset:64
	global_store_dword v171, v49, s[28:29] offset:0
	s_waitcnt vmcnt(29)
	v_sub_f32_e32 v233, v237, v160
	v_mul_f32_e32 v233, v233, v161
	v_fma_f32 v233, v239, v233, v243
	v_cndmask_b32_e64 v237, v237, v233, s[98:99]
	v_mul_f32_e32 v50, v50, v173
	v_fmac_f32_e32 v50, 0x3fb504f3, v237
	global_load_dword v237, v172, s[2:3] offset:-4032
	global_store_dword v172, v50, s[28:29] offset:-4096
	s_waitcnt vmcnt(30)
	v_sub_f32_e32 v233, v238, v162
	v_mul_f32_e32 v233, v233, v163
	v_fma_f32 v233, v239, v233, v243
	v_cndmask_b32_e64 v238, v238, v233, s[98:99]
	v_mul_f32_e32 v51, v51, v173
	v_fmac_f32_e32 v51, 0x3fb504f3, v238
	global_load_dword v238, v172, s[2:3] offset:64
	global_store_dword v172, v51, s[28:29] offset:0
	s_waitcnt vmcnt(31)
	v_sub_f32_e32 v233, v177, v132
	v_mul_f32_e32 v233, v233, v133
	v_fma_f32 v233, v240, v233, v244
	v_cndmask_b32_e64 v177, v177, v233, s[98:99]
	v_mul_f32_e32 v4, v4, v174
	v_fmac_f32_e32 v4, 0x3fb504f3, v177
	global_load_dword v177, v165, s[2:3] offset:-3968
	global_store_dword v165, v4, s[28:29] offset:-4032
	s_waitcnt vmcnt(31)
	v_sub_f32_e32 v233, v178, v134
	v_mul_f32_e32 v233, v233, v135
	v_fma_f32 v233, v240, v233, v244
	v_cndmask_b32_e64 v178, v178, v233, s[98:99]
	v_mul_f32_e32 v5, v5, v174
	v_fmac_f32_e32 v5, 0x3fb504f3, v178
	global_load_dword v178, v165, s[2:3] offset:128
	global_store_dword v165, v5, s[28:29] offset:64
	s_waitcnt vmcnt(31)
	v_sub_f32_e32 v233, v179, v136
	v_mul_f32_e32 v233, v233, v137
	v_fma_f32 v233, v240, v233, v244
	v_cndmask_b32_e64 v179, v179, v233, s[98:99]
	v_mul_f32_e32 v6, v6, v174
	v_fmac_f32_e32 v6, 0x3fb504f3, v179
	global_load_dword v179, v166, s[2:3] offset:-3968
	global_store_dword v166, v6, s[28:29] offset:-4032
	s_waitcnt vmcnt(31)
	v_sub_f32_e32 v233, v224, v138
	v_mul_f32_e32 v233, v233, v139
	v_fma_f32 v233, v240, v233, v244
	v_cndmask_b32_e64 v224, v224, v233, s[98:99]
	v_mul_f32_e32 v7, v7, v174
	v_fmac_f32_e32 v7, 0x3fb504f3, v224
	global_load_dword v224, v166, s[2:3] offset:128
	global_store_dword v166, v7, s[28:29] offset:64
	s_waitcnt vmcnt(31)
	v_sub_f32_e32 v233, v225, v140
	v_mul_f32_e32 v233, v233, v141
	v_fma_f32 v233, v240, v233, v244
	v_cndmask_b32_e64 v225, v225, v233, s[98:99]
	v_mul_f32_e32 v20, v20, v174
	v_fmac_f32_e32 v20, 0x3fb504f3, v225
	global_load_dword v225, v167, s[2:3] offset:-3968
	global_store_dword v167, v20, s[28:29] offset:-4032
	s_waitcnt vmcnt(31)
	v_sub_f32_e32 v233, v226, v142
	v_mul_f32_e32 v233, v233, v143
	v_fma_f32 v233, v240, v233, v244
	v_cndmask_b32_e64 v226, v226, v233, s[98:99]
	v_mul_f32_e32 v21, v21, v174
	v_fmac_f32_e32 v21, 0x3fb504f3, v226
	global_load_dword v226, v167, s[2:3] offset:128
	global_store_dword v167, v21, s[28:29] offset:64
	s_waitcnt vmcnt(31)
	v_sub_f32_e32 v233, v227, v144
	v_mul_f32_e32 v233, v233, v145
	v_fma_f32 v233, v240, v233, v244
	v_cndmask_b32_e64 v227, v227, v233, s[98:99]
	v_mul_f32_e32 v22, v22, v174
	v_fmac_f32_e32 v22, 0x3fb504f3, v227
	global_load_dword v227, v168, s[2:3] offset:-3968
	global_store_dword v168, v22, s[28:29] offset:-4032
	s_waitcnt vmcnt(31)
	v_sub_f32_e32 v233, v228, v146
	v_mul_f32_e32 v233, v233, v147
	v_fma_f32 v233, v240, v233, v244
	v_cndmask_b32_e64 v228, v228, v233, s[98:99]
	v_mul_f32_e32 v23, v23, v174
	v_fmac_f32_e32 v23, 0x3fb504f3, v228
	global_load_dword v228, v168, s[2:3] offset:128
	global_store_dword v168, v23, s[28:29] offset:64
	s_waitcnt vmcnt(31)
	v_sub_f32_e32 v233, v229, v148
	v_mul_f32_e32 v233, v233, v149
	v_fma_f32 v233, v240, v233, v244
	v_cndmask_b32_e64 v229, v229, v233, s[98:99]
	v_mul_f32_e32 v36, v36, v174
	v_fmac_f32_e32 v36, 0x3fb504f3, v229
	global_load_dword v229, v169, s[2:3] offset:-3968
	global_store_dword v169, v36, s[28:29] offset:-4032
	s_waitcnt vmcnt(31)
	v_sub_f32_e32 v233, v230, v150
	v_mul_f32_e32 v233, v233, v151
	v_fma_f32 v233, v240, v233, v244
	v_cndmask_b32_e64 v230, v230, v233, s[98:99]
	v_mul_f32_e32 v37, v37, v174
	v_fmac_f32_e32 v37, 0x3fb504f3, v230
	global_load_dword v230, v169, s[2:3] offset:128
	global_store_dword v169, v37, s[28:29] offset:64
	s_waitcnt vmcnt(31)
	v_sub_f32_e32 v233, v231, v152
	v_mul_f32_e32 v233, v233, v153
	v_fma_f32 v233, v240, v233, v244
	v_cndmask_b32_e64 v231, v231, v233, s[98:99]
	v_mul_f32_e32 v38, v38, v174
	v_fmac_f32_e32 v38, 0x3fb504f3, v231
	global_load_dword v231, v170, s[2:3] offset:-3968
	global_store_dword v170, v38, s[28:29] offset:-4032
	s_waitcnt vmcnt(31)
	v_sub_f32_e32 v233, v234, v154
	v_mul_f32_e32 v233, v233, v155
	v_fma_f32 v233, v240, v233, v244
	v_cndmask_b32_e64 v234, v234, v233, s[98:99]
	v_mul_f32_e32 v39, v39, v174
	v_fmac_f32_e32 v39, 0x3fb504f3, v234
	global_load_dword v234, v170, s[2:3] offset:128
	global_store_dword v170, v39, s[28:29] offset:64
	s_waitcnt vmcnt(31)
	v_sub_f32_e32 v233, v235, v156
	v_mul_f32_e32 v233, v233, v157
	v_fma_f32 v233, v240, v233, v244
	v_cndmask_b32_e64 v235, v235, v233, s[98:99]
	v_mul_f32_e32 v52, v52, v174
	v_fmac_f32_e32 v52, 0x3fb504f3, v235
	global_load_dword v235, v171, s[2:3] offset:-3968
	global_store_dword v171, v52, s[28:29] offset:-4032
	s_waitcnt vmcnt(31)
	v_sub_f32_e32 v233, v236, v158
	v_mul_f32_e32 v233, v233, v159
	v_fma_f32 v233, v240, v233, v244
	v_cndmask_b32_e64 v236, v236, v233, s[98:99]
	v_mul_f32_e32 v53, v53, v174
	v_fmac_f32_e32 v53, 0x3fb504f3, v236
	global_load_dword v236, v171, s[2:3] offset:128
	global_store_dword v171, v53, s[28:29] offset:64
	s_waitcnt vmcnt(31)
	v_sub_f32_e32 v233, v237, v160
	v_mul_f32_e32 v233, v233, v161
	v_fma_f32 v233, v240, v233, v244
	v_cndmask_b32_e64 v237, v237, v233, s[98:99]
	v_mul_f32_e32 v54, v54, v174
	v_fmac_f32_e32 v54, 0x3fb504f3, v237
	global_load_dword v237, v172, s[2:3] offset:-3968
	global_store_dword v172, v54, s[28:29] offset:-4032
	s_waitcnt vmcnt(31)
	v_sub_f32_e32 v233, v238, v162
	v_mul_f32_e32 v233, v233, v163
	v_fma_f32 v233, v240, v233, v244
	v_cndmask_b32_e64 v238, v238, v233, s[98:99]
	v_mul_f32_e32 v55, v55, v174
	v_fmac_f32_e32 v55, 0x3fb504f3, v238
	global_load_dword v238, v172, s[2:3] offset:128
	global_store_dword v172, v55, s[28:29] offset:64
	s_waitcnt vmcnt(31)
	v_sub_f32_e32 v233, v177, v132
	v_mul_f32_e32 v233, v233, v133
	v_fma_f32 v233, v241, v233, v245
	v_cndmask_b32_e64 v177, v177, v233, s[98:99]
	v_mul_f32_e32 v8, v8, v175
	v_fmac_f32_e32 v8, 0x3fb504f3, v177
	global_load_dword v177, v165, s[2:3] offset:-3904
	global_store_dword v165, v8, s[28:29] offset:-3968
	s_waitcnt vmcnt(31)
	v_sub_f32_e32 v233, v178, v134
	v_mul_f32_e32 v233, v233, v135
	v_fma_f32 v233, v241, v233, v245
	v_cndmask_b32_e64 v178, v178, v233, s[98:99]
	v_mul_f32_e32 v9, v9, v175
	v_fmac_f32_e32 v9, 0x3fb504f3, v178
	global_load_dword v178, v165, s[2:3] offset:192
	global_store_dword v165, v9, s[28:29] offset:128
	s_waitcnt vmcnt(31)
	v_sub_f32_e32 v233, v179, v136
	v_mul_f32_e32 v233, v233, v137
	v_fma_f32 v233, v241, v233, v245
	v_cndmask_b32_e64 v179, v179, v233, s[98:99]
	v_mul_f32_e32 v10, v10, v175
	v_fmac_f32_e32 v10, 0x3fb504f3, v179
	global_load_dword v179, v166, s[2:3] offset:-3904
	global_store_dword v166, v10, s[28:29] offset:-3968
	s_waitcnt vmcnt(31)
	v_sub_f32_e32 v233, v224, v138
	v_mul_f32_e32 v233, v233, v139
	v_fma_f32 v233, v241, v233, v245
	v_cndmask_b32_e64 v224, v224, v233, s[98:99]
	v_mul_f32_e32 v11, v11, v175
	v_fmac_f32_e32 v11, 0x3fb504f3, v224
	global_load_dword v224, v166, s[2:3] offset:192
	global_store_dword v166, v11, s[28:29] offset:128
	s_waitcnt vmcnt(31)
	v_sub_f32_e32 v233, v225, v140
	v_mul_f32_e32 v233, v233, v141
	v_fma_f32 v233, v241, v233, v245
	v_cndmask_b32_e64 v225, v225, v233, s[98:99]
	v_mul_f32_e32 v24, v24, v175
	v_fmac_f32_e32 v24, 0x3fb504f3, v225
	global_load_dword v225, v167, s[2:3] offset:-3904
	global_store_dword v167, v24, s[28:29] offset:-3968
	s_waitcnt vmcnt(31)
	v_sub_f32_e32 v233, v226, v142
	v_mul_f32_e32 v233, v233, v143
	v_fma_f32 v233, v241, v233, v245
	v_cndmask_b32_e64 v226, v226, v233, s[98:99]
	v_mul_f32_e32 v25, v25, v175
	v_fmac_f32_e32 v25, 0x3fb504f3, v226
	global_load_dword v226, v167, s[2:3] offset:192
	global_store_dword v167, v25, s[28:29] offset:128
	s_waitcnt vmcnt(31)
	v_sub_f32_e32 v233, v227, v144
	v_mul_f32_e32 v233, v233, v145
	v_fma_f32 v233, v241, v233, v245
	v_cndmask_b32_e64 v227, v227, v233, s[98:99]
	v_mul_f32_e32 v26, v26, v175
	v_fmac_f32_e32 v26, 0x3fb504f3, v227
	global_load_dword v227, v168, s[2:3] offset:-3904
	global_store_dword v168, v26, s[28:29] offset:-3968
	s_waitcnt vmcnt(31)
	v_sub_f32_e32 v233, v228, v146
	v_mul_f32_e32 v233, v233, v147
	v_fma_f32 v233, v241, v233, v245
	v_cndmask_b32_e64 v228, v228, v233, s[98:99]
	v_mul_f32_e32 v27, v27, v175
	v_fmac_f32_e32 v27, 0x3fb504f3, v228
	global_load_dword v228, v168, s[2:3] offset:192
	global_store_dword v168, v27, s[28:29] offset:128
	s_waitcnt vmcnt(31)
	v_sub_f32_e32 v233, v229, v148
	v_mul_f32_e32 v233, v233, v149
	v_fma_f32 v233, v241, v233, v245
	v_cndmask_b32_e64 v229, v229, v233, s[98:99]
	v_mul_f32_e32 v40, v40, v175
	v_fmac_f32_e32 v40, 0x3fb504f3, v229
	global_load_dword v229, v169, s[2:3] offset:-3904
	global_store_dword v169, v40, s[28:29] offset:-3968
	s_waitcnt vmcnt(31)
	v_sub_f32_e32 v233, v230, v150
	v_mul_f32_e32 v233, v233, v151
	v_fma_f32 v233, v241, v233, v245
	v_cndmask_b32_e64 v230, v230, v233, s[98:99]
	v_mul_f32_e32 v41, v41, v175
	v_fmac_f32_e32 v41, 0x3fb504f3, v230
	global_load_dword v230, v169, s[2:3] offset:192
	global_store_dword v169, v41, s[28:29] offset:128
	s_waitcnt vmcnt(31)
	v_sub_f32_e32 v233, v231, v152
	v_mul_f32_e32 v233, v233, v153
	v_fma_f32 v233, v241, v233, v245
	v_cndmask_b32_e64 v231, v231, v233, s[98:99]
	v_mul_f32_e32 v42, v42, v175
	v_fmac_f32_e32 v42, 0x3fb504f3, v231
	global_load_dword v231, v170, s[2:3] offset:-3904
	global_store_dword v170, v42, s[28:29] offset:-3968
	s_waitcnt vmcnt(31)
	v_sub_f32_e32 v233, v234, v154
	v_mul_f32_e32 v233, v233, v155
	v_fma_f32 v233, v241, v233, v245
	v_cndmask_b32_e64 v234, v234, v233, s[98:99]
	v_mul_f32_e32 v43, v43, v175
	v_fmac_f32_e32 v43, 0x3fb504f3, v234
	global_load_dword v234, v170, s[2:3] offset:192
	global_store_dword v170, v43, s[28:29] offset:128
	s_waitcnt vmcnt(31)
	v_sub_f32_e32 v233, v235, v156
	v_mul_f32_e32 v233, v233, v157
	v_fma_f32 v233, v241, v233, v245
	v_cndmask_b32_e64 v235, v235, v233, s[98:99]
	v_mul_f32_e32 v56, v56, v175
	v_fmac_f32_e32 v56, 0x3fb504f3, v235
	global_load_dword v235, v171, s[2:3] offset:-3904
	global_store_dword v171, v56, s[28:29] offset:-3968
	s_waitcnt vmcnt(31)
	v_sub_f32_e32 v233, v236, v158
	v_mul_f32_e32 v233, v233, v159
	v_fma_f32 v233, v241, v233, v245
	v_cndmask_b32_e64 v236, v236, v233, s[98:99]
	v_mul_f32_e32 v57, v57, v175
	v_fmac_f32_e32 v57, 0x3fb504f3, v236
	global_load_dword v236, v171, s[2:3] offset:192
	global_store_dword v171, v57, s[28:29] offset:128
	s_waitcnt vmcnt(31)
	v_sub_f32_e32 v233, v237, v160
	v_mul_f32_e32 v233, v233, v161
	v_fma_f32 v233, v241, v233, v245
	v_cndmask_b32_e64 v237, v237, v233, s[98:99]
	v_mul_f32_e32 v58, v58, v175
	v_fmac_f32_e32 v58, 0x3fb504f3, v237
	global_load_dword v237, v172, s[2:3] offset:-3904
	global_store_dword v172, v58, s[28:29] offset:-3968
	s_waitcnt vmcnt(31)
	v_sub_f32_e32 v233, v238, v162
	v_mul_f32_e32 v233, v233, v163
	v_fma_f32 v233, v241, v233, v245
	v_cndmask_b32_e64 v238, v238, v233, s[98:99]
	v_mul_f32_e32 v59, v59, v175
	v_fmac_f32_e32 v59, 0x3fb504f3, v238
	global_load_dword v238, v172, s[2:3] offset:192
	global_store_dword v172, v59, s[28:29] offset:128
	s_waitcnt vmcnt(31)
	v_sub_f32_e32 v233, v177, v132
	v_mul_f32_e32 v233, v233, v133
	v_fma_f32 v233, v242, v233, v112
	v_cndmask_b32_e64 v177, v177, v233, s[98:99]
	v_mul_f32_e32 v12, v12, v176
	v_fmac_f32_e32 v12, 0x3fb504f3, v177
	global_store_dword v165, v12, s[28:29] offset:-3904
	s_waitcnt vmcnt(30)
	v_sub_f32_e32 v233, v178, v134
	v_mul_f32_e32 v233, v233, v135
	v_fma_f32 v233, v242, v233, v112
	v_cndmask_b32_e64 v178, v178, v233, s[98:99]
	v_mul_f32_e32 v13, v13, v176
	v_fmac_f32_e32 v13, 0x3fb504f3, v178
	global_store_dword v165, v13, s[28:29] offset:192
	s_waitcnt vmcnt(29)
	v_sub_f32_e32 v233, v179, v136
	v_mul_f32_e32 v233, v233, v137
	v_fma_f32 v233, v242, v233, v112
	v_cndmask_b32_e64 v179, v179, v233, s[98:99]
	v_mul_f32_e32 v14, v14, v176
	v_fmac_f32_e32 v14, 0x3fb504f3, v179
	global_store_dword v166, v14, s[28:29] offset:-3904
	s_waitcnt vmcnt(28)
	v_sub_f32_e32 v233, v224, v138
	v_mul_f32_e32 v233, v233, v139
	v_fma_f32 v233, v242, v233, v112
	v_cndmask_b32_e64 v224, v224, v233, s[98:99]
	v_mul_f32_e32 v15, v15, v176
	v_fmac_f32_e32 v15, 0x3fb504f3, v224
	global_store_dword v166, v15, s[28:29] offset:192
	s_waitcnt vmcnt(27)
	v_sub_f32_e32 v233, v225, v140
	v_mul_f32_e32 v233, v233, v141
	v_fma_f32 v233, v242, v233, v112
	v_cndmask_b32_e64 v225, v225, v233, s[98:99]
	v_mul_f32_e32 v28, v28, v176
	v_fmac_f32_e32 v28, 0x3fb504f3, v225
	global_store_dword v167, v28, s[28:29] offset:-3904
	s_waitcnt vmcnt(26)
	v_sub_f32_e32 v233, v226, v142
	v_mul_f32_e32 v233, v233, v143
	v_fma_f32 v233, v242, v233, v112
	v_cndmask_b32_e64 v226, v226, v233, s[98:99]
	v_mul_f32_e32 v29, v29, v176
	v_fmac_f32_e32 v29, 0x3fb504f3, v226
	global_store_dword v167, v29, s[28:29] offset:192
	s_waitcnt vmcnt(25)
	v_sub_f32_e32 v233, v227, v144
	v_mul_f32_e32 v233, v233, v145
	v_fma_f32 v233, v242, v233, v112
	v_cndmask_b32_e64 v227, v227, v233, s[98:99]
	v_mul_f32_e32 v30, v30, v176
	v_fmac_f32_e32 v30, 0x3fb504f3, v227
	global_store_dword v168, v30, s[28:29] offset:-3904
	s_waitcnt vmcnt(24)
	v_sub_f32_e32 v233, v228, v146
	v_mul_f32_e32 v233, v233, v147
	v_fma_f32 v233, v242, v233, v112
	v_cndmask_b32_e64 v228, v228, v233, s[98:99]
	v_mul_f32_e32 v31, v31, v176
	v_fmac_f32_e32 v31, 0x3fb504f3, v228
	global_store_dword v168, v31, s[28:29] offset:192
	s_waitcnt vmcnt(23)
	v_sub_f32_e32 v233, v229, v148
	v_mul_f32_e32 v233, v233, v149
	v_fma_f32 v233, v242, v233, v112
	v_cndmask_b32_e64 v229, v229, v233, s[98:99]
	v_mul_f32_e32 v44, v44, v176
	v_fmac_f32_e32 v44, 0x3fb504f3, v229
	global_store_dword v169, v44, s[28:29] offset:-3904
	s_waitcnt vmcnt(22)
	v_sub_f32_e32 v233, v230, v150
	v_mul_f32_e32 v233, v233, v151
	v_fma_f32 v233, v242, v233, v112
	v_cndmask_b32_e64 v230, v230, v233, s[98:99]
	v_mul_f32_e32 v45, v45, v176
	v_fmac_f32_e32 v45, 0x3fb504f3, v230
	global_store_dword v169, v45, s[28:29] offset:192
	s_waitcnt vmcnt(21)
	v_sub_f32_e32 v233, v231, v152
	v_mul_f32_e32 v233, v233, v153
	v_fma_f32 v233, v242, v233, v112
	v_cndmask_b32_e64 v231, v231, v233, s[98:99]
	v_mul_f32_e32 v46, v46, v176
	v_fmac_f32_e32 v46, 0x3fb504f3, v231
	global_store_dword v170, v46, s[28:29] offset:-3904
	s_waitcnt vmcnt(20)
	v_sub_f32_e32 v233, v234, v154
	v_mul_f32_e32 v233, v233, v155
	v_fma_f32 v233, v242, v233, v112
	v_cndmask_b32_e64 v234, v234, v233, s[98:99]
	v_mul_f32_e32 v47, v47, v176
	v_fmac_f32_e32 v47, 0x3fb504f3, v234
	global_store_dword v170, v47, s[28:29] offset:192
	s_waitcnt vmcnt(19)
	v_sub_f32_e32 v233, v235, v156
	v_mul_f32_e32 v233, v233, v157
	v_fma_f32 v233, v242, v233, v112
	v_cndmask_b32_e64 v235, v235, v233, s[98:99]
	v_mul_f32_e32 v60, v60, v176
	v_fmac_f32_e32 v60, 0x3fb504f3, v235
	global_store_dword v171, v60, s[28:29] offset:-3904
	s_waitcnt vmcnt(18)
	v_sub_f32_e32 v233, v236, v158
	v_mul_f32_e32 v233, v233, v159
	v_fma_f32 v233, v242, v233, v112
	v_cndmask_b32_e64 v236, v236, v233, s[98:99]
	v_mul_f32_e32 v61, v61, v176
	v_fmac_f32_e32 v61, 0x3fb504f3, v236
	global_store_dword v171, v61, s[28:29] offset:192
	s_waitcnt vmcnt(17)
	v_sub_f32_e32 v233, v237, v160
	v_mul_f32_e32 v233, v233, v161
	v_fma_f32 v233, v242, v233, v112
	v_cndmask_b32_e64 v237, v237, v233, s[98:99]
	v_mul_f32_e32 v62, v62, v176
	v_fmac_f32_e32 v62, 0x3fb504f3, v237
	global_store_dword v172, v62, s[28:29] offset:-3904
	s_waitcnt vmcnt(16)
	v_sub_f32_e32 v233, v238, v162
	v_mul_f32_e32 v233, v233, v163
	v_fma_f32 v233, v242, v233, v112
	v_cndmask_b32_e64 v238, v238, v233, s[98:99]
	v_mul_f32_e32 v63, v63, v176
	v_fmac_f32_e32 v63, 0x3fb504f3, v238
	global_store_dword v172, v63, s[28:29] offset:192
	v_add_u32_e32 v180, 64, v180
	v_lshl_add_u32 v164, v180, 12, v181
	v_add_u32_e32 v165, 0x1000, v164
	v_add_u32_e32 v166, 0x3000, v164
	v_add_u32_e32 v167, 0x11000, v164
	v_add_u32_e32 v168, 0x13000, v164
	v_add_u32_e32 v169, 0x21000, v164
	v_add_u32_e32 v170, 0x23000, v164
	v_add_u32_e32 v171, 0x31000, v164
	v_add_u32_e32 v172, 0x33000, v164
	v_lshlrev_b32_e32 v35, 3, v180
	v_add_u32_e32 v35, 0x1e200000, v35
	v_add_u32_e32 v48, 0x2000, v181
	v_mov_b32_e32 v49, s71
	v_cmp_ne_u32_e64 s[98:99], 0, v49
	global_load_dwordx2 v[132:133], v35, s[30:31] offset:0
	global_load_dwordx2 v[134:135], v35, s[30:31] offset:8
	global_load_dwordx2 v[136:137], v35, s[30:31] offset:16
	global_load_dwordx2 v[138:139], v35, s[30:31] offset:24
	global_load_dwordx2 v[140:141], v35, s[30:31] offset:128
	global_load_dwordx2 v[142:143], v35, s[30:31] offset:136
	global_load_dwordx2 v[144:145], v35, s[30:31] offset:144
	global_load_dwordx2 v[146:147], v35, s[30:31] offset:152
	global_load_dwordx2 v[148:149], v35, s[30:31] offset:256
	global_load_dwordx2 v[150:151], v35, s[30:31] offset:264
	global_load_dwordx2 v[152:153], v35, s[30:31] offset:272
	global_load_dwordx2 v[154:155], v35, s[30:31] offset:280
	global_load_dwordx2 v[156:157], v35, s[30:31] offset:384
	global_load_dwordx2 v[158:159], v35, s[30:31] offset:392
	global_load_dwordx2 v[160:161], v35, s[30:31] offset:400
	global_load_dwordx2 v[162:163], v35, s[30:31] offset:408
	global_load_dword v3, v48, s[24:25] offset:0
	global_load_dword v19, v48, s[26:27] offset:0
	global_load_dword v16, v48, s[24:25] offset:64
	global_load_dword v32, v48, s[26:27] offset:64
	global_load_dword v17, v48, s[24:25] offset:128
	global_load_dword v33, v48, s[26:27] offset:128
	global_load_dword v18, v48, s[24:25] offset:192
	global_load_dword v34, v48, s[26:27] offset:192
	global_load_dword v173, v[246:247], off offset:0
	global_load_dword v174, v[246:247], off offset:64
	global_load_dword v175, v[246:247], off offset:128
	global_load_dword v176, v[246:247], off offset:192
	global_load_dword v177, v165, s[2:3] offset:-4096
	global_load_dword v178, v165, s[2:3] offset:0
	global_load_dword v179, v166, s[2:3] offset:-4096
	global_load_dword v224, v166, s[2:3] offset:0
	global_load_dword v225, v167, s[2:3] offset:-4096
	global_load_dword v226, v167, s[2:3] offset:0
	global_load_dword v227, v168, s[2:3] offset:-4096
	global_load_dword v228, v168, s[2:3] offset:0
	global_load_dword v229, v169, s[2:3] offset:-4096
	global_load_dword v230, v169, s[2:3] offset:0
	global_load_dword v231, v170, s[2:3] offset:-4096
	global_load_dword v234, v170, s[2:3] offset:0
	global_load_dword v235, v171, s[2:3] offset:-4096
	global_load_dword v236, v171, s[2:3] offset:0
	global_load_dword v237, v172, s[2:3] offset:-4096
	global_load_dword v238, v172, s[2:3] offset:0
	global_load_dword v239, v165, s[2:3] offset:-4032
	global_load_dword v240, v165, s[2:3] offset:64
	global_load_dword v241, v166, s[2:3] offset:-4032
	global_load_dword v242, v166, s[2:3] offset:64
	global_load_dword v243, v167, s[2:3] offset:-4032
	global_load_dword v244, v167, s[2:3] offset:64
	global_load_dword v245, v168, s[2:3] offset:-4032
	global_load_dword v112, v168, s[2:3] offset:64
	global_load_dword v115, v169, s[2:3] offset:-4032
	global_load_dword v208, v169, s[2:3] offset:64
	global_load_dword v223, v170, s[2:3] offset:-4032
	global_load_dword v233, v170, s[2:3] offset:64
	global_load_dword v248, v171, s[2:3] offset:-4032
	global_load_dword v0, v171, s[2:3] offset:64
	global_load_dword v1, v172, s[2:3] offset:-4032
	global_load_dword v2, v172, s[2:3] offset:64
	s_waitcnt vmcnt(31)
	v_add_f32_e32 v173, 1.0, v173
	v_add_f32_e32 v174, 1.0, v174
	v_add_f32_e32 v175, 1.0, v175
	v_add_f32_e32 v176, 1.0, v176
	v_mul_f32_e32 v173, 0.5, v173
	v_mul_f32_e32 v174, 0.5, v174
	v_mul_f32_e32 v175, 0.5, v175
	v_mul_f32_e32 v176, 0.5, v176
	v_sub_f32_e32 v50, v177, v132
	v_mul_f32_e32 v50, v50, v133
	v_fma_f32 v50, v3, v50, v19
	v_cndmask_b32_e64 v177, v177, v50, s[98:99]
	v_mul_f32_e32 v64, v64, v173
	v_fmac_f32_e32 v64, 0x3fb504f3, v177
	global_load_dword v177, v165, s[2:3] offset:-3968
	global_store_dword v165, v64, s[28:29] offset:-4096
	s_waitcnt vmcnt(32)
	v_sub_f32_e32 v50, v178, v134
	v_mul_f32_e32 v50, v50, v135
	v_fma_f32 v50, v3, v50, v19
	v_cndmask_b32_e64 v178, v178, v50, s[98:99]
	v_mul_f32_e32 v65, v65, v173
	v_fmac_f32_e32 v65, 0x3fb504f3, v178
	global_load_dword v178, v165, s[2:3] offset:128
	global_store_dword v165, v65, s[28:29] offset:0
	s_waitcnt vmcnt(33)
	v_sub_f32_e32 v50, v179, v136
	v_mul_f32_e32 v50, v50, v137
	v_fma_f32 v50, v3, v50, v19
	v_cndmask_b32_e64 v179, v179, v50, s[98:99]
	v_mul_f32_e32 v66, v66, v173
	v_fmac_f32_e32 v66, 0x3fb504f3, v179
	global_load_dword v179, v166, s[2:3] offset:-3968
	global_store_dword v166, v66, s[28:29] offset:-4096
	s_waitcnt vmcnt(34)
	v_sub_f32_e32 v50, v224, v138
	v_mul_f32_e32 v50, v50, v139
	v_fma_f32 v50, v3, v50, v19
	v_cndmask_b32_e64 v224, v224, v50, s[98:99]
	v_mul_f32_e32 v67, v67, v173
	v_fmac_f32_e32 v67, 0x3fb504f3, v224
	global_load_dword v224, v166, s[2:3] offset:128
	global_store_dword v166, v67, s[28:29] offset:0
	s_waitcnt vmcnt(35)
	v_sub_f32_e32 v50, v225, v140
	v_mul_f32_e32 v50, v50, v141
	v_fma_f32 v50, v3, v50, v19
	v_cndmask_b32_e64 v225, v225, v50, s[98:99]
	v_mul_f32_e32 v80, v80, v173
	v_fmac_f32_e32 v80, 0x3fb504f3, v225
	global_load_dword v225, v167, s[2:3] offset:-3968
	global_store_dword v167, v80, s[28:29] offset:-4096
	s_waitcnt vmcnt(36)
	v_sub_f32_e32 v50, v226, v142
	v_mul_f32_e32 v50, v50, v143
	v_fma_f32 v50, v3, v50, v19
	v_cndmask_b32_e64 v226, v226, v50, s[98:99]
	v_mul_f32_e32 v81, v81, v173
	v_fmac_f32_e32 v81, 0x3fb504f3, v226
	global_load_dword v226, v167, s[2:3] offset:128
	global_store_dword v167, v81, s[28:29] offset:0
	s_waitcnt vmcnt(37)
	v_sub_f32_e32 v50, v227, v144
	v_mul_f32_e32 v50, v50, v145
	v_fma_f32 v50, v3, v50, v19
	v_cndmask_b32_e64 v227, v227, v50, s[98:99]
	v_mul_f32_e32 v82, v82, v173
	v_fmac_f32_e32 v82, 0x3fb504f3, v227
	global_load_dword v227, v168, s[2:3] offset:-3968
	global_store_dword v168, v82, s[28:29] offset:-4096
	s_waitcnt vmcnt(38)
	v_sub_f32_e32 v50, v228, v146
	v_mul_f32_e32 v50, v50, v147
	v_fma_f32 v50, v3, v50, v19
	v_cndmask_b32_e64 v228, v228, v50, s[98:99]
	v_mul_f32_e32 v83, v83, v173
	v_fmac_f32_e32 v83, 0x3fb504f3, v228
	global_load_dword v228, v168, s[2:3] offset:128
	global_store_dword v168, v83, s[28:29] offset:0
	s_waitcnt vmcnt(39)
	v_sub_f32_e32 v50, v229, v148
	v_mul_f32_e32 v50, v50, v149
	v_fma_f32 v50, v3, v50, v19
	v_cndmask_b32_e64 v229, v229, v50, s[98:99]
	v_mul_f32_e32 v96, v96, v173
	v_fmac_f32_e32 v96, 0x3fb504f3, v229
	global_load_dword v229, v169, s[2:3] offset:-3968
	global_store_dword v169, v96, s[28:29] offset:-4096
	s_waitcnt vmcnt(40)
	v_sub_f32_e32 v50, v230, v150
	v_mul_f32_e32 v50, v50, v151
	v_fma_f32 v50, v3, v50, v19
	v_cndmask_b32_e64 v230, v230, v50, s[98:99]
	v_mul_f32_e32 v97, v97, v173
	v_fmac_f32_e32 v97, 0x3fb504f3, v230
	global_load_dword v230, v169, s[2:3] offset:128
	global_store_dword v169, v97, s[28:29] offset:0
	s_waitcnt vmcnt(41)
	v_sub_f32_e32 v50, v231, v152
	v_mul_f32_e32 v50, v50, v153
	v_fma_f32 v50, v3, v50, v19
	v_cndmask_b32_e64 v231, v231, v50, s[98:99]
	v_mul_f32_e32 v98, v98, v173
	v_fmac_f32_e32 v98, 0x3fb504f3, v231
	global_load_dword v231, v170, s[2:3] offset:-3968
	global_store_dword v170, v98, s[28:29] offset:-4096
	s_waitcnt vmcnt(42)
	v_sub_f32_e32 v50, v234, v154
	v_mul_f32_e32 v50, v50, v155
	v_fma_f32 v50, v3, v50, v19
	v_cndmask_b32_e64 v234, v234, v50, s[98:99]
	v_mul_f32_e32 v99, v99, v173
	v_fmac_f32_e32 v99, 0x3fb504f3, v234
	global_load_dword v234, v170, s[2:3] offset:128
	global_store_dword v170, v99, s[28:29] offset:0
	s_waitcnt vmcnt(43)
	v_sub_f32_e32 v50, v235, v156
	v_mul_f32_e32 v50, v50, v157
	v_fma_f32 v50, v3, v50, v19
	v_cndmask_b32_e64 v235, v235, v50, s[98:99]
	v_mul_f32_e32 v116, v116, v173
	v_fmac_f32_e32 v116, 0x3fb504f3, v235
	global_load_dword v235, v171, s[2:3] offset:-3968
	global_store_dword v171, v116, s[28:29] offset:-4096
	s_waitcnt vmcnt(44)
	v_sub_f32_e32 v50, v236, v158
	v_mul_f32_e32 v50, v50, v159
	v_fma_f32 v50, v3, v50, v19
	v_cndmask_b32_e64 v236, v236, v50, s[98:99]
	v_mul_f32_e32 v117, v117, v173
	v_fmac_f32_e32 v117, 0x3fb504f3, v236
	global_load_dword v236, v171, s[2:3] offset:128
	global_store_dword v171, v117, s[28:29] offset:0
	s_waitcnt vmcnt(45)
	v_sub_f32_e32 v50, v237, v160
	v_mul_f32_e32 v50, v50, v161
	v_fma_f32 v50, v3, v50, v19
	v_cndmask_b32_e64 v237, v237, v50, s[98:99]
	v_mul_f32_e32 v118, v118, v173
	v_fmac_f32_e32 v118, 0x3fb504f3, v237
	global_load_dword v237, v172, s[2:3] offset:-3968
	global_store_dword v172, v118, s[28:29] offset:-4096
	s_waitcnt vmcnt(46)
	v_sub_f32_e32 v50, v238, v162
	v_mul_f32_e32 v50, v50, v163
	v_fma_f32 v50, v3, v50, v19
	v_cndmask_b32_e64 v238, v238, v50, s[98:99]
	v_mul_f32_e32 v119, v119, v173
	v_fmac_f32_e32 v119, 0x3fb504f3, v238
	global_load_dword v238, v172, s[2:3] offset:128
	global_store_dword v172, v119, s[28:29] offset:0
	s_waitcnt vmcnt(47)
	v_sub_f32_e32 v50, v239, v132
	v_mul_f32_e32 v50, v50, v133
	v_fma_f32 v50, v16, v50, v32
	v_cndmask_b32_e64 v239, v239, v50, s[98:99]
	v_mul_f32_e32 v68, v68, v174
	v_fmac_f32_e32 v68, 0x3fb504f3, v239
	global_load_dword v239, v165, s[2:3] offset:-3904
	global_store_dword v165, v68, s[28:29] offset:-4032
	s_waitcnt vmcnt(48)
	v_sub_f32_e32 v50, v240, v134
	v_mul_f32_e32 v50, v50, v135
	v_fma_f32 v50, v16, v50, v32
	v_cndmask_b32_e64 v240, v240, v50, s[98:99]
	v_mul_f32_e32 v69, v69, v174
	v_fmac_f32_e32 v69, 0x3fb504f3, v240
	global_load_dword v240, v165, s[2:3] offset:192
	global_store_dword v165, v69, s[28:29] offset:64
	s_waitcnt vmcnt(49)
	v_sub_f32_e32 v50, v241, v136
	v_mul_f32_e32 v50, v50, v137
	v_fma_f32 v50, v16, v50, v32
	v_cndmask_b32_e64 v241, v241, v50, s[98:99]
	v_mul_f32_e32 v70, v70, v174
	v_fmac_f32_e32 v70, 0x3fb504f3, v241
	global_load_dword v241, v166, s[2:3] offset:-3904
	global_store_dword v166, v70, s[28:29] offset:-4032
	s_waitcnt vmcnt(50)
	v_sub_f32_e32 v50, v242, v138
	v_mul_f32_e32 v50, v50, v139
	v_fma_f32 v50, v16, v50, v32
	v_cndmask_b32_e64 v242, v242, v50, s[98:99]
	v_mul_f32_e32 v71, v71, v174
	v_fmac_f32_e32 v71, 0x3fb504f3, v242
	global_load_dword v242, v166, s[2:3] offset:192
	global_store_dword v166, v71, s[28:29] offset:64
	s_waitcnt vmcnt(51)
	v_sub_f32_e32 v50, v243, v140
	v_mul_f32_e32 v50, v50, v141
	v_fma_f32 v50, v16, v50, v32
	v_cndmask_b32_e64 v243, v243, v50, s[98:99]
	v_mul_f32_e32 v84, v84, v174
	v_fmac_f32_e32 v84, 0x3fb504f3, v243
	global_load_dword v243, v167, s[2:3] offset:-3904
	global_store_dword v167, v84, s[28:29] offset:-4032
	s_waitcnt vmcnt(52)
	v_sub_f32_e32 v50, v244, v142
	v_mul_f32_e32 v50, v50, v143
	v_fma_f32 v50, v16, v50, v32
	v_cndmask_b32_e64 v244, v244, v50, s[98:99]
	v_mul_f32_e32 v85, v85, v174
	v_fmac_f32_e32 v85, 0x3fb504f3, v244
	global_load_dword v244, v167, s[2:3] offset:192
	global_store_dword v167, v85, s[28:29] offset:64
	s_waitcnt vmcnt(53)
	v_sub_f32_e32 v50, v245, v144
	v_mul_f32_e32 v50, v50, v145
	v_fma_f32 v50, v16, v50, v32
	v_cndmask_b32_e64 v245, v245, v50, s[98:99]
	v_mul_f32_e32 v86, v86, v174
	v_fmac_f32_e32 v86, 0x3fb504f3, v245
	global_load_dword v245, v168, s[2:3] offset:-3904
	global_store_dword v168, v86, s[28:29] offset:-4032
	s_waitcnt vmcnt(54)
	v_sub_f32_e32 v50, v112, v146
	v_mul_f32_e32 v50, v50, v147
	v_fma_f32 v50, v16, v50, v32
	v_cndmask_b32_e64 v112, v112, v50, s[98:99]
	v_mul_f32_e32 v87, v87, v174
	v_fmac_f32_e32 v87, 0x3fb504f3, v112
	global_load_dword v112, v168, s[2:3] offset:192
	global_store_dword v168, v87, s[28:29] offset:64
	s_waitcnt vmcnt(55)
	v_sub_f32_e32 v50, v115, v148
	v_mul_f32_e32 v50, v50, v149
	v_fma_f32 v50, v16, v50, v32
	v_cndmask_b32_e64 v115, v115, v50, s[98:99]
	v_mul_f32_e32 v100, v100, v174
	v_fmac_f32_e32 v100, 0x3fb504f3, v115
	global_load_dword v115, v169, s[2:3] offset:-3904
	global_store_dword v169, v100, s[28:29] offset:-4032
	s_waitcnt vmcnt(56)
	v_sub_f32_e32 v50, v208, v150
	v_mul_f32_e32 v50, v50, v151
	v_fma_f32 v50, v16, v50, v32
	v_cndmask_b32_e64 v208, v208, v50, s[98:99]
	v_mul_f32_e32 v101, v101, v174
	v_fmac_f32_e32 v101, 0x3fb504f3, v208
	global_load_dword v208, v169, s[2:3] offset:192
	global_store_dword v169, v101, s[28:29] offset:64
	s_waitcnt vmcnt(57)
	v_sub_f32_e32 v50, v223, v152
	v_mul_f32_e32 v50, v50, v153
	v_fma_f32 v50, v16, v50, v32
	v_cndmask_b32_e64 v223, v223, v50, s[98:99]
	v_mul_f32_e32 v102, v102, v174
	v_fmac_f32_e32 v102, 0x3fb504f3, v223
	global_load_dword v223, v170, s[2:3] offset:-3904
	global_store_dword v170, v102, s[28:29] offset:-4032
	s_waitcnt vmcnt(58)
	v_sub_f32_e32 v50, v233, v154
	v_mul_f32_e32 v50, v50, v155
	v_fma_f32 v50, v16, v50, v32
	v_cndmask_b32_e64 v233, v233, v50, s[98:99]
	v_mul_f32_e32 v103, v103, v174
	v_fmac_f32_e32 v103, 0x3fb504f3, v233
	global_load_dword v233, v170, s[2:3] offset:192
	global_store_dword v170, v103, s[28:29] offset:64
	s_waitcnt vmcnt(59)
	v_sub_f32_e32 v50, v248, v156
	v_mul_f32_e32 v50, v50, v157
	v_fma_f32 v50, v16, v50, v32
	v_cndmask_b32_e64 v248, v248, v50, s[98:99]
	v_mul_f32_e32 v120, v120, v174
	v_fmac_f32_e32 v120, 0x3fb504f3, v248
	global_load_dword v248, v171, s[2:3] offset:-3904
	global_store_dword v171, v120, s[28:29] offset:-4032
	s_waitcnt vmcnt(60)
	v_sub_f32_e32 v50, v0, v158
	v_mul_f32_e32 v50, v50, v159
	v_fma_f32 v50, v16, v50, v32
	v_cndmask_b32_e64 v0, v0, v50, s[98:99]
	v_mul_f32_e32 v121, v121, v174
	v_fmac_f32_e32 v121, 0x3fb504f3, v0
	global_load_dword v0, v171, s[2:3] offset:192
	global_store_dword v171, v121, s[28:29] offset:64
	s_waitcnt vmcnt(61)
	v_sub_f32_e32 v50, v1, v160
	v_mul_f32_e32 v50, v50, v161
	v_fma_f32 v50, v16, v50, v32
	v_cndmask_b32_e64 v1, v1, v50, s[98:99]
	v_mul_f32_e32 v122, v122, v174
	v_fmac_f32_e32 v122, 0x3fb504f3, v1
	global_load_dword v1, v172, s[2:3] offset:-3904
	global_store_dword v172, v122, s[28:29] offset:-4032
	s_waitcnt vmcnt(62)
	v_sub_f32_e32 v50, v2, v162
	v_mul_f32_e32 v50, v50, v163
	v_fma_f32 v50, v16, v50, v32
	v_cndmask_b32_e64 v2, v2, v50, s[98:99]
	v_mul_f32_e32 v123, v123, v174
	v_fmac_f32_e32 v123, 0x3fb504f3, v2
	global_load_dword v2, v172, s[2:3] offset:192
	global_store_dword v172, v123, s[28:29] offset:64
	s_waitcnt vmcnt(63)
	v_sub_f32_e32 v50, v177, v132
	v_mul_f32_e32 v50, v50, v133
	v_fma_f32 v50, v17, v50, v33
	v_cndmask_b32_e64 v177, v177, v50, s[98:99]
	v_mul_f32_e32 v72, v72, v175
	v_fmac_f32_e32 v72, 0x3fb504f3, v177
	global_store_dword v165, v72, s[28:29] offset:-3968
	s_waitcnt vmcnt(62)
	v_sub_f32_e32 v50, v178, v134
	v_mul_f32_e32 v50, v50, v135
	v_fma_f32 v50, v17, v50, v33
	v_cndmask_b32_e64 v178, v178, v50, s[98:99]
	v_mul_f32_e32 v73, v73, v175
	v_fmac_f32_e32 v73, 0x3fb504f3, v178
	global_store_dword v165, v73, s[28:29] offset:128
	s_waitcnt vmcnt(61)
	v_sub_f32_e32 v50, v179, v136
	v_mul_f32_e32 v50, v50, v137
	v_fma_f32 v50, v17, v50, v33
	v_cndmask_b32_e64 v179, v179, v50, s[98:99]
	v_mul_f32_e32 v74, v74, v175
	v_fmac_f32_e32 v74, 0x3fb504f3, v179
	global_store_dword v166, v74, s[28:29] offset:-3968
	s_waitcnt vmcnt(60)
	v_sub_f32_e32 v50, v224, v138
	v_mul_f32_e32 v50, v50, v139
	v_fma_f32 v50, v17, v50, v33
	v_cndmask_b32_e64 v224, v224, v50, s[98:99]
	v_mul_f32_e32 v75, v75, v175
	v_fmac_f32_e32 v75, 0x3fb504f3, v224
	global_store_dword v166, v75, s[28:29] offset:128
	s_waitcnt vmcnt(59)
	v_sub_f32_e32 v50, v225, v140
	v_mul_f32_e32 v50, v50, v141
	v_fma_f32 v50, v17, v50, v33
	v_cndmask_b32_e64 v225, v225, v50, s[98:99]
	v_mul_f32_e32 v88, v88, v175
	v_fmac_f32_e32 v88, 0x3fb504f3, v225
	global_store_dword v167, v88, s[28:29] offset:-3968
	s_waitcnt vmcnt(58)
	v_sub_f32_e32 v50, v226, v142
	v_mul_f32_e32 v50, v50, v143
	v_fma_f32 v50, v17, v50, v33
	v_cndmask_b32_e64 v226, v226, v50, s[98:99]
	v_mul_f32_e32 v89, v89, v175
	v_fmac_f32_e32 v89, 0x3fb504f3, v226
	global_store_dword v167, v89, s[28:29] offset:128
	s_waitcnt vmcnt(57)
	v_sub_f32_e32 v50, v227, v144
	v_mul_f32_e32 v50, v50, v145
	v_fma_f32 v50, v17, v50, v33
	v_cndmask_b32_e64 v227, v227, v50, s[98:99]
	v_mul_f32_e32 v90, v90, v175
	v_fmac_f32_e32 v90, 0x3fb504f3, v227
	global_store_dword v168, v90, s[28:29] offset:-3968
	s_waitcnt vmcnt(56)
	v_sub_f32_e32 v50, v228, v146
	v_mul_f32_e32 v50, v50, v147
	v_fma_f32 v50, v17, v50, v33
	v_cndmask_b32_e64 v228, v228, v50, s[98:99]
	v_mul_f32_e32 v91, v91, v175
	v_fmac_f32_e32 v91, 0x3fb504f3, v228
	global_store_dword v168, v91, s[28:29] offset:128
	s_waitcnt vmcnt(55)
	v_sub_f32_e32 v50, v229, v148
	v_mul_f32_e32 v50, v50, v149
	v_fma_f32 v50, v17, v50, v33
	v_cndmask_b32_e64 v229, v229, v50, s[98:99]
	v_mul_f32_e32 v104, v104, v175
	v_fmac_f32_e32 v104, 0x3fb504f3, v229
	global_store_dword v169, v104, s[28:29] offset:-3968
	s_waitcnt vmcnt(54)
	v_sub_f32_e32 v50, v230, v150
	v_mul_f32_e32 v50, v50, v151
	v_fma_f32 v50, v17, v50, v33
	v_cndmask_b32_e64 v230, v230, v50, s[98:99]
	v_mul_f32_e32 v105, v105, v175
	v_fmac_f32_e32 v105, 0x3fb504f3, v230
	global_store_dword v169, v105, s[28:29] offset:128
	s_waitcnt vmcnt(53)
	v_sub_f32_e32 v50, v231, v152
	v_mul_f32_e32 v50, v50, v153
	v_fma_f32 v50, v17, v50, v33
	v_cndmask_b32_e64 v231, v231, v50, s[98:99]
	v_mul_f32_e32 v106, v106, v175
	v_fmac_f32_e32 v106, 0x3fb504f3, v231
	global_store_dword v170, v106, s[28:29] offset:-3968
	s_waitcnt vmcnt(52)
	v_sub_f32_e32 v50, v234, v154
	v_mul_f32_e32 v50, v50, v155
	v_fma_f32 v50, v17, v50, v33
	v_cndmask_b32_e64 v234, v234, v50, s[98:99]
	v_mul_f32_e32 v107, v107, v175
	v_fmac_f32_e32 v107, 0x3fb504f3, v234
	global_store_dword v170, v107, s[28:29] offset:128
	s_waitcnt vmcnt(51)
	v_sub_f32_e32 v50, v235, v156
	v_mul_f32_e32 v50, v50, v157
	v_fma_f32 v50, v17, v50, v33
	v_cndmask_b32_e64 v235, v235, v50, s[98:99]
	v_mul_f32_e32 v124, v124, v175
	v_fmac_f32_e32 v124, 0x3fb504f3, v235
	global_store_dword v171, v124, s[28:29] offset:-3968
	s_waitcnt vmcnt(50)
	v_sub_f32_e32 v50, v236, v158
	v_mul_f32_e32 v50, v50, v159
	v_fma_f32 v50, v17, v50, v33
	v_cndmask_b32_e64 v236, v236, v50, s[98:99]
	v_mul_f32_e32 v125, v125, v175
	v_fmac_f32_e32 v125, 0x3fb504f3, v236
	global_store_dword v171, v125, s[28:29] offset:128
	s_waitcnt vmcnt(49)
	v_sub_f32_e32 v50, v237, v160
	v_mul_f32_e32 v50, v50, v161
	v_fma_f32 v50, v17, v50, v33
	v_cndmask_b32_e64 v237, v237, v50, s[98:99]
	v_mul_f32_e32 v126, v126, v175
	v_fmac_f32_e32 v126, 0x3fb504f3, v237
	global_store_dword v172, v126, s[28:29] offset:-3968
	s_waitcnt vmcnt(48)
	v_sub_f32_e32 v50, v238, v162
	v_mul_f32_e32 v50, v50, v163
	v_fma_f32 v50, v17, v50, v33
	v_cndmask_b32_e64 v238, v238, v50, s[98:99]
	v_mul_f32_e32 v127, v127, v175
	v_fmac_f32_e32 v127, 0x3fb504f3, v238
	global_store_dword v172, v127, s[28:29] offset:128
	s_waitcnt vmcnt(47)
	v_sub_f32_e32 v50, v239, v132
	v_mul_f32_e32 v50, v50, v133
	v_fma_f32 v50, v18, v50, v34
	v_cndmask_b32_e64 v239, v239, v50, s[98:99]
	v_mul_f32_e32 v76, v76, v176
	v_fmac_f32_e32 v76, 0x3fb504f3, v239
	global_store_dword v165, v76, s[28:29] offset:-3904
	s_waitcnt vmcnt(46)
	v_sub_f32_e32 v50, v240, v134
	v_mul_f32_e32 v50, v50, v135
	v_fma_f32 v50, v18, v50, v34
	v_cndmask_b32_e64 v240, v240, v50, s[98:99]
	v_mul_f32_e32 v77, v77, v176
	v_fmac_f32_e32 v77, 0x3fb504f3, v240
	global_store_dword v165, v77, s[28:29] offset:192
	s_waitcnt vmcnt(45)
	v_sub_f32_e32 v50, v241, v136
	v_mul_f32_e32 v50, v50, v137
	v_fma_f32 v50, v18, v50, v34
	v_cndmask_b32_e64 v241, v241, v50, s[98:99]
	v_mul_f32_e32 v78, v78, v176
	v_fmac_f32_e32 v78, 0x3fb504f3, v241
	global_store_dword v166, v78, s[28:29] offset:-3904
	s_waitcnt vmcnt(44)
	v_sub_f32_e32 v50, v242, v138
	v_mul_f32_e32 v50, v50, v139
	v_fma_f32 v50, v18, v50, v34
	v_cndmask_b32_e64 v242, v242, v50, s[98:99]
	v_mul_f32_e32 v79, v79, v176
	v_fmac_f32_e32 v79, 0x3fb504f3, v242
	global_store_dword v166, v79, s[28:29] offset:192
	s_waitcnt vmcnt(43)
	v_sub_f32_e32 v50, v243, v140
	v_mul_f32_e32 v50, v50, v141
	v_fma_f32 v50, v18, v50, v34
	v_cndmask_b32_e64 v243, v243, v50, s[98:99]
	v_mul_f32_e32 v92, v92, v176
	v_fmac_f32_e32 v92, 0x3fb504f3, v243
	global_store_dword v167, v92, s[28:29] offset:-3904
	s_waitcnt vmcnt(42)
	v_sub_f32_e32 v50, v244, v142
	v_mul_f32_e32 v50, v50, v143
	v_fma_f32 v50, v18, v50, v34
	v_cndmask_b32_e64 v244, v244, v50, s[98:99]
	v_mul_f32_e32 v93, v93, v176
	v_fmac_f32_e32 v93, 0x3fb504f3, v244
	global_store_dword v167, v93, s[28:29] offset:192
	s_waitcnt vmcnt(41)
	v_sub_f32_e32 v50, v245, v144
	v_mul_f32_e32 v50, v50, v145
	v_fma_f32 v50, v18, v50, v34
	v_cndmask_b32_e64 v245, v245, v50, s[98:99]
	v_mul_f32_e32 v94, v94, v176
	v_fmac_f32_e32 v94, 0x3fb504f3, v245
	global_store_dword v168, v94, s[28:29] offset:-3904
	s_waitcnt vmcnt(40)
	v_sub_f32_e32 v50, v112, v146
	v_mul_f32_e32 v50, v50, v147
	v_fma_f32 v50, v18, v50, v34
	v_cndmask_b32_e64 v112, v112, v50, s[98:99]
	v_mul_f32_e32 v95, v95, v176
	v_fmac_f32_e32 v95, 0x3fb504f3, v112
	global_store_dword v168, v95, s[28:29] offset:192
	s_waitcnt vmcnt(39)
	v_sub_f32_e32 v50, v115, v148
	v_mul_f32_e32 v50, v50, v149
	v_fma_f32 v50, v18, v50, v34
	v_cndmask_b32_e64 v115, v115, v50, s[98:99]
	v_mul_f32_e32 v108, v108, v176
	v_fmac_f32_e32 v108, 0x3fb504f3, v115
	global_store_dword v169, v108, s[28:29] offset:-3904
	s_waitcnt vmcnt(38)
	v_sub_f32_e32 v50, v208, v150
	v_mul_f32_e32 v50, v50, v151
	v_fma_f32 v50, v18, v50, v34
	v_cndmask_b32_e64 v208, v208, v50, s[98:99]
	v_mul_f32_e32 v109, v109, v176
	v_fmac_f32_e32 v109, 0x3fb504f3, v208
	global_store_dword v169, v109, s[28:29] offset:192
	s_waitcnt vmcnt(37)
	v_sub_f32_e32 v50, v223, v152
	v_mul_f32_e32 v50, v50, v153
	v_fma_f32 v50, v18, v50, v34
	v_cndmask_b32_e64 v223, v223, v50, s[98:99]
	v_mul_f32_e32 v110, v110, v176
	v_fmac_f32_e32 v110, 0x3fb504f3, v223
	global_store_dword v170, v110, s[28:29] offset:-3904
	s_waitcnt vmcnt(36)
	v_sub_f32_e32 v50, v233, v154
	v_mul_f32_e32 v50, v50, v155
	v_fma_f32 v50, v18, v50, v34
	v_cndmask_b32_e64 v233, v233, v50, s[98:99]
	v_mul_f32_e32 v111, v111, v176
	v_fmac_f32_e32 v111, 0x3fb504f3, v233
	global_store_dword v170, v111, s[28:29] offset:192
	s_waitcnt vmcnt(35)
	v_sub_f32_e32 v50, v248, v156
	v_mul_f32_e32 v50, v50, v157
	v_fma_f32 v50, v18, v50, v34
	v_cndmask_b32_e64 v248, v248, v50, s[98:99]
	v_mul_f32_e32 v128, v128, v176
	v_fmac_f32_e32 v128, 0x3fb504f3, v248
	global_store_dword v171, v128, s[28:29] offset:-3904
	s_waitcnt vmcnt(34)
	v_sub_f32_e32 v50, v0, v158
	v_mul_f32_e32 v50, v50, v159
	v_fma_f32 v50, v18, v50, v34
	v_cndmask_b32_e64 v0, v0, v50, s[98:99]
	v_mul_f32_e32 v129, v129, v176
	v_fmac_f32_e32 v129, 0x3fb504f3, v0
	global_store_dword v171, v129, s[28:29] offset:192
	s_waitcnt vmcnt(33)
	v_sub_f32_e32 v50, v1, v160
	v_mul_f32_e32 v50, v50, v161
	v_fma_f32 v50, v18, v50, v34
	v_cndmask_b32_e64 v1, v1, v50, s[98:99]
	v_mul_f32_e32 v130, v130, v176
	v_fmac_f32_e32 v130, 0x3fb504f3, v1
	global_store_dword v172, v130, s[28:29] offset:-3904
	s_waitcnt vmcnt(32)
	v_sub_f32_e32 v50, v2, v162
	v_mul_f32_e32 v50, v50, v163
	v_fma_f32 v50, v18, v50, v34
	v_cndmask_b32_e64 v2, v2, v50, s[98:99]
	v_mul_f32_e32 v131, v131, v176
	v_fmac_f32_e32 v131, 0x3fb504f3, v2
	global_store_dword v172, v131, s[28:29] offset:192
	s_add_i32 s13, s13, s59
	s_cmpk_gt_i32 s13, 0x3ff
	s_cbranch_scc0 .LBB0_153
	v_mov_b32_e32 v113, 0
	v_mov_b32_e32 v114, 0x3f317218

.LBB0_612:
	s_cmp_ge_i32 s0, s52
	s_cselect_b64 s[2:3], -1, 0
	s_cmp_lt_i32 s0, s53
	s_cselect_b64 s[4:5], -1, 0
	s_and_b64 s[2:3], s[2:3], s[4:5]
	s_andn2_b64 vcc, exec, s[2:3]
	s_cbranch_vccnz .LBB0_619
	s_waitcnt vmcnt(17)
	v_mov_b32_e32 v32, v182
	v_readlane_b32 s0, v251, 17
	v_ashrrev_i32_e32 v0, 6, v32
	s_nop 0
	v_add_u32_e32 v0, s0, v0
	v_readlane_b32 s0, v250, 31
	s_nop 1
	v_mul_lo_u32 v48, v0, s0
	v_add_u32_e32 v0, s0, v48
	v_min_i32_e32 v72, 0x8000, v0
	v_cmp_lt_i32_e32 vcc, v48, v72
	s_and_saveexec_b64 s[2:3], vcc
	s_cbranch_execz .LBB0_618
	v_lshlrev_b32_e32 v0, 2, v32
	s_mul_i32 s0, s71, 0xc00
	v_and_b32_e32 v33, 0xfc, v0
	s_addk_i32 s0, 0x400
	v_or_b32_e32 v0, s0, v33
	v_ashrrev_i32_e32 v1, 31, v0
	v_lshlrev_b64 v[0:1], 2, v[0:1]
	v_lshl_add_u64 v[20:21], s[24:25], 0, v[0:1]
	v_lshl_add_u64 v[28:29], s[26:27], 0, v[0:1]
	global_load_dwordx4 v[0:3], v[20:21], off
	global_load_dwordx4 v[4:7], v[20:21], off offset:1024
	global_load_dwordx4 v[8:11], v[28:29], off
	global_load_dwordx4 v[12:15], v[28:29], off offset:1024
	global_load_dwordx4 v[16:19], v[20:21], off offset:2048
	s_nop 0
	global_load_dwordx4 v[20:23], v[20:21], off offset:3072
	s_nop 0
	global_load_dwordx4 v[24:27], v[28:29], off offset:2048
	s_nop 0
	global_load_dwordx4 v[28:31], v[28:29], off offset:3072
	v_and_b32_e32 v34, 64, v196
	v_add_u32_e32 v34, 64, v34
	v_xor_b32_e32 v35, 1, v196
	v_cmp_lt_i32_e32 vcc, v35, v34
	v_ashrrev_i32_e32 v49, 31, v48
	v_lshlrev_b32_e32 v112, 2, v33
	v_cndmask_b32_e32 v35, v196, v35, vcc
	v_lshlrev_b32_e32 v73, 2, v35
	v_xor_b32_e32 v35, 2, v196
	v_cmp_lt_i32_e32 vcc, v35, v34
	v_and_b32_e32 v36, 63, v32
	v_lshlrev_b64 v[32:33], 12, v[48:49]
	v_cndmask_b32_e32 v35, v196, v35, vcc
	v_lshlrev_b32_e32 v74, 2, v35
	v_xor_b32_e32 v35, 4, v196
	v_cmp_lt_i32_e32 vcc, v35, v34
	v_readlane_b32 s4, v250, 41
	v_lshl_or_b32 v32, v36, 4, v32
	v_cndmask_b32_e32 v35, v196, v35, vcc
	v_lshlrev_b32_e32 v75, 2, v35
	v_xor_b32_e32 v35, 8, v196
	v_cmp_lt_i32_e32 vcc, v35, v34
	v_readlane_b32 s5, v250, 42
	s_lshl_b32 s0, s71, 2
	v_cndmask_b32_e32 v35, v196, v35, vcc
	v_lshlrev_b32_e32 v76, 2, v35
	v_xor_b32_e32 v35, 16, v196
	v_cmp_lt_i32_e32 vcc, v35, v34
	v_mov_b32_e32 v79, -1
	v_lshl_add_u64 v[50:51], s[50:51], 0, v[112:113]
	v_cndmask_b32_e32 v35, v196, v35, vcc
	v_lshlrev_b32_e32 v77, 2, v35
	v_xor_b32_e32 v35, 32, v196
	v_cmp_lt_i32_e32 vcc, v35, v34
	v_lshl_add_u64 v[54:55], s[4:5], 0, v[32:33]
	s_mov_b64 s[8:9], 0
	v_cndmask_b32_e32 v34, v196, v35, vcc
	v_lshlrev_b32_e32 v78, 2, v34
	v_lshlrev_b64 v[34:35], 11, v[48:49]
	v_lshl_or_b32 v34, v36, 3, v34
	v_lshl_add_u64 v[52:53], s[40:41], 0, v[34:35]
	global_load_dwordx4 v[136:139], v[54:55], off offset:-2048
	global_load_dwordx4 v[140:143], v[54:55], off offset:-1024
	global_load_dwordx4 v[144:147], v[54:55], off
	global_load_dwordx4 v[148:151], v[54:55], off offset:1024
	s_branch .LBB0_616
.LBB0_615:
	s_or_b64 exec, exec, s[10:11]
	s_waitcnt vmcnt(5)
	v_mov_b32_e32 v80, v136
	v_mov_b32_e32 v81, v137
	v_mov_b32_e32 v82, v138
	v_mov_b32_e32 v83, v139
	v_mov_b32_e32 v84, v140
	v_mov_b32_e32 v85, v141
	v_mov_b32_e32 v86, v142
	v_mov_b32_e32 v87, v143
	v_mov_b32_e32 v88, v144
	v_mov_b32_e32 v89, v145
	v_mov_b32_e32 v90, v146
	v_mov_b32_e32 v91, v147
	v_mov_b32_e32 v92, v148
	v_mov_b32_e32 v93, v149
	v_mov_b32_e32 v94, v150
	v_mov_b32_e32 v95, v151
	v_add_u32_e32 v48, 1, v48
	v_mov_b32_e32 v154, 0x1000
	v_cmp_lt_i32_e32 vcc, v48, v72
	s_nop 1
	v_cndmask_b32_e32 v154, 0, v154, vcc
	v_add_co_u32_e32 v152, vcc, v54, v154
	s_nop 1
	v_addc_co_u32_e32 v153, vcc, 0, v55, vcc
	global_load_dwordx4 v[136:139], v[152:153], off offset:-2048
	global_load_dwordx4 v[140:143], v[152:153], off offset:-1024
	global_load_dwordx4 v[144:147], v[152:153], off
	global_load_dwordx4 v[148:151], v[152:153], off offset:1024
	s_mov_b64 s[4:5], 0x800
	v_add_f32_e32 v49, 0, v80
	v_add_f32_e32 v49, v49, v81
	v_add_f32_e32 v49, v49, v82
	v_add_f32_e32 v49, v49, v83
	v_add_f32_e32 v49, v49, v84
	v_add_f32_e32 v49, v49, v85
	v_add_f32_e32 v49, v49, v86
	v_add_f32_e32 v49, v49, v87
	v_add_f32_e32 v49, v49, v88
	v_add_f32_e32 v49, v49, v89
	v_add_f32_e32 v49, v49, v90
	v_add_f32_e32 v49, v49, v91
	v_add_f32_e32 v49, v49, v92
	v_add_f32_e32 v49, v49, v93
	v_add_f32_e32 v49, v49, v94
	v_add_f32_e32 v49, v49, v95
	ds_bpermute_b32 v96, v73, v49
	s_waitcnt lgkmcnt(0)
	v_add_f32_e32 v49, v49, v96
	ds_bpermute_b32 v96, v74, v49
	s_waitcnt lgkmcnt(0)
	v_add_f32_e32 v49, v49, v96
	ds_bpermute_b32 v96, v75, v49
	s_waitcnt lgkmcnt(0)
	v_add_f32_e32 v49, v49, v96
	ds_bpermute_b32 v96, v76, v49
	s_waitcnt lgkmcnt(0)
	v_add_f32_e32 v49, v49, v96
	ds_bpermute_b32 v96, v77, v49
	s_waitcnt lgkmcnt(0)
	v_add_f32_e32 v49, v49, v96
	ds_bpermute_b32 v96, v78, v49
	s_waitcnt lgkmcnt(0)
	v_add_f32_e32 v49, v49, v96
	v_mul_f32_e32 v96, 0x3a800000, v49
	v_mov_b32_e32 v252, v96
	v_pk_add_f32 v[80:81], v[80:81], v[96:97] op_sel_hi:[1,0] neg_lo:[0,1] neg_hi:[0,1]
	v_pk_add_f32 v[82:83], v[82:83], v[96:97] op_sel_hi:[1,0] neg_lo:[0,1] neg_hi:[0,1]
	v_pk_mul_f32 v[98:99], v[80:81], v[80:81]
	v_pk_mul_f32 v[100:101], v[82:83], v[82:83]
	v_add_f32_e32 v49, v98, v99
	v_pk_add_f32 v[84:85], v[84:85], v[96:97] op_sel_hi:[1,0] neg_lo:[0,1] neg_hi:[0,1]
	v_add_f32_e32 v49, v100, v49
	v_pk_mul_f32 v[102:103], v[84:85], v[84:85]
	v_add_f32_e32 v49, v101, v49
	v_pk_add_f32 v[86:87], v[86:87], v[96:97] op_sel_hi:[1,0] neg_lo:[0,1] neg_hi:[0,1]
	v_add_f32_e32 v49, v102, v49
	v_pk_mul_f32 v[104:105], v[86:87], v[86:87]
	v_add_f32_e32 v49, v103, v49
	v_pk_add_f32 v[88:89], v[88:89], v[96:97] op_sel_hi:[1,0] neg_lo:[0,1] neg_hi:[0,1]
	v_add_f32_e32 v49, v104, v49
	v_pk_mul_f32 v[106:107], v[88:89], v[88:89]
	v_add_f32_e32 v49, v105, v49
	v_pk_add_f32 v[90:91], v[90:91], v[96:97] op_sel_hi:[1,0] neg_lo:[0,1] neg_hi:[0,1]
	v_add_f32_e32 v49, v106, v49
	v_pk_mul_f32 v[108:109], v[90:91], v[90:91]
	v_add_f32_e32 v49, v107, v49
	v_pk_add_f32 v[92:93], v[92:93], v[96:97] op_sel_hi:[1,0] neg_lo:[0,1] neg_hi:[0,1]
	v_add_f32_e32 v49, v108, v49
	v_pk_mul_f32 v[110:111], v[92:93], v[92:93]
	v_add_f32_e32 v49, v109, v49
	v_pk_add_f32 v[94:95], v[94:95], v[96:97] op_sel_hi:[1,0] neg_lo:[0,1] neg_hi:[0,1]
	v_add_f32_e32 v49, v110, v49
	v_pk_mul_f32 v[96:97], v[94:95], v[94:95]
	v_add_f32_e32 v49, v111, v49
	v_add_f32_e32 v49, v96, v49
	v_add_f32_e32 v49, v97, v49
	ds_bpermute_b32 v96, v73, v49
	s_waitcnt lgkmcnt(0)
	v_add_f32_e32 v49, v49, v96
	ds_bpermute_b32 v96, v74, v49
	s_waitcnt lgkmcnt(0)
	v_add_f32_e32 v49, v49, v96
	ds_bpermute_b32 v96, v75, v49
	s_waitcnt lgkmcnt(0)
	v_add_f32_e32 v49, v49, v96
	ds_bpermute_b32 v96, v76, v49
	s_waitcnt lgkmcnt(0)
	v_add_f32_e32 v49, v49, v96
	ds_bpermute_b32 v96, v77, v49
	s_waitcnt lgkmcnt(0)
	v_add_f32_e32 v49, v49, v96
	ds_bpermute_b32 v96, v78, v49
	s_waitcnt lgkmcnt(0)
	v_add_f32_e32 v49, v49, v96
	v_fmamk_f32 v49, v49, 0x3a800000, v184
	v_cmp_gt_f32_e32 vcc, s49, v49
	v_mul_f32_e32 v96, 0x4b800000, v49
	s_nop 0
	v_cndmask_b32_e32 v49, v49, v96, vcc
	v_rsq_f32_e32 v49, v49
	s_nop 0
	v_mul_f32_e32 v96, 0x45800000, v49
	v_cndmask_b32_e32 v96, v49, v96, vcc
	v_mov_b32_e32 v253, v96
	v_lshlrev_b32_e32 v254, 3, v48
	v_add_u32_e32 v254, 0x1e1ffff8, v254
	s_mov_b64 exec, 1
	global_store_dwordx2 v254, v[252:253], s[30:31]
	s_mov_b64 exec, -1
	v_pk_mul_f32 v[80:81], v[80:81], v[96:97] op_sel_hi:[1,0]
	v_pk_mul_f32 v[82:83], v[82:83], v[96:97] op_sel_hi:[1,0]
	v_pk_fma_f32 v[80:81], v[0:1], v[80:81], v[8:9]
	v_pk_fma_f32 v[82:83], v[2:3], v[82:83], v[10:11]
	v_pk_mul_f32 v[84:85], v[84:85], v[96:97] op_sel_hi:[1,0]
	v_pk_mul_f32 v[86:87], v[86:87], v[96:97] op_sel_hi:[1,0]
	v_pk_mul_f32 v[88:89], v[88:89], v[96:97] op_sel_hi:[1,0]
	v_pk_mul_f32 v[90:91], v[90:91], v[96:97] op_sel_hi:[1,0]
	v_pk_mul_f32 v[92:93], v[92:93], v[96:97] op_sel_hi:[1,0]
	v_pk_mul_f32 v[94:95], v[94:95], v[96:97] op_sel_hi:[1,0]
	v_pk_fma_f32 v[84:85], v[4:5], v[84:85], v[12:13]
	v_pk_fma_f32 v[86:87], v[6:7], v[86:87], v[14:15]
	v_pk_fma_f32 v[88:89], v[16:17], v[88:89], v[24:25]
	v_pk_fma_f32 v[90:91], v[18:19], v[90:91], v[26:27]
	v_pk_fma_f32 v[92:93], v[20:21], v[92:93], v[28:29]
	v_pk_fma_f32 v[94:95], v[22:23], v[94:95], v[30:31]
	v_pk_fma_f32 v[80:81], v[66:67], v[80:81], v[44:45]
	v_cmp_ge_i32_e32 vcc, v48, v72
	v_med3_f32 v49, v80, s57, v194
	v_med3_f32 v96, v81, s57, v194
	v_pk_fma_f32 v[80:81], v[64:65], v[82:83], v[46:47]
	s_or_b64 s[8:9], vcc, s[8:9]
	v_med3_f32 v80, v80, s57, v194
	v_med3_f32 v81, v81, s57, v194
	v_cvt_pk_f16_f32 v49, v49, v80
	v_cvt_pk_f16_f32 v80, v96, v81
	v_and_b32_e32 v81, 0xffff0000, v80
	v_lshlrev_b32_e32 v80, 16, v80
	v_or_b32_sdwa v81, v81, v49 dst_sel:DWORD dst_unused:UNUSED_PAD src0_sel:DWORD src1_sel:WORD_1
	v_or_b32_sdwa v80, v80, v49 dst_sel:DWORD dst_unused:UNUSED_PAD src0_sel:DWORD src1_sel:WORD_0
	global_store_dwordx2 v[52:53], v[80:81], off
	v_pk_fma_f32 v[80:81], v[62:63], v[84:85], v[40:41]
	s_nop 0
	v_med3_f32 v49, v80, s57, v194
	v_med3_f32 v82, v81, s57, v194
	v_pk_fma_f32 v[80:81], v[60:61], v[86:87], v[42:43]
	s_nop 0
	v_med3_f32 v80, v80, s57, v194
	v_med3_f32 v81, v81, s57, v194
	v_cvt_pk_f16_f32 v49, v49, v80
	v_cvt_pk_f16_f32 v80, v82, v81
	v_and_b32_e32 v81, 0xffff0000, v80
	v_lshlrev_b32_e32 v80, 16, v80
	v_or_b32_sdwa v81, v81, v49 dst_sel:DWORD dst_unused:UNUSED_PAD src0_sel:DWORD src1_sel:WORD_1
	v_or_b32_sdwa v80, v80, v49 dst_sel:DWORD dst_unused:UNUSED_PAD src0_sel:DWORD src1_sel:WORD_0
	global_store_dwordx2 v[52:53], v[80:81], off offset:512
	v_pk_fma_f32 v[80:81], v[58:59], v[88:89], v[36:37]
	s_nop 0
	v_med3_f32 v49, v80, s57, v194
	v_med3_f32 v82, v81, s57, v194
	v_pk_fma_f32 v[80:81], v[56:57], v[90:91], v[38:39]
	s_nop 0
	v_med3_f32 v80, v80, s57, v194
	v_med3_f32 v81, v81, s57, v194
	v_cvt_pk_f16_f32 v49, v49, v80
	v_cvt_pk_f16_f32 v80, v82, v81
	v_and_b32_e32 v81, 0xffff0000, v80
	v_lshlrev_b32_e32 v80, 16, v80
	v_or_b32_sdwa v81, v81, v49 dst_sel:DWORD dst_unused:UNUSED_PAD src0_sel:DWORD src1_sel:WORD_1
	v_or_b32_sdwa v80, v80, v49 dst_sel:DWORD dst_unused:UNUSED_PAD src0_sel:DWORD src1_sel:WORD_0
	global_store_dwordx2 v[52:53], v[80:81], off offset:1024
	v_pk_fma_f32 v[80:81], v[70:71], v[92:93], v[32:33]
	s_nop 0
	v_med3_f32 v49, v80, s57, v194
	v_med3_f32 v82, v81, s57, v194
	v_pk_fma_f32 v[80:81], v[68:69], v[94:95], v[34:35]
	s_nop 0
	v_med3_f32 v80, v80, s57, v194
	v_med3_f32 v81, v81, s57, v194
	v_cvt_pk_f16_f32 v49, v49, v80
	v_cvt_pk_f16_f32 v80, v82, v81
	v_and_b32_e32 v81, 0xffff0000, v80
	v_lshlrev_b32_e32 v80, 16, v80
	v_or_b32_sdwa v81, v81, v49 dst_sel:DWORD dst_unused:UNUSED_PAD src0_sel:DWORD src1_sel:WORD_1
	v_or_b32_sdwa v80, v80, v49 dst_sel:DWORD dst_unused:UNUSED_PAD src0_sel:DWORD src1_sel:WORD_0
	global_store_dwordx2 v[52:53], v[80:81], off offset:1536
	v_lshl_add_u64 v[52:53], v[52:53], 0, s[4:5]
	s_mov_b64 s[4:5], 0x1000
	v_lshl_add_u64 v[54:55], v[54:55], 0, s[4:5]
	s_andn2_b64 exec, exec, s[8:9]
	s_cbranch_execz .LBB0_618
.LBB0_616:
	v_ashrrev_i32_e32 v49, 31, v48
	v_lshrrev_b32_e32 v49, 19, v49
	v_add_u32_e32 v49, v48, v49
	v_ashrrev_i32_e32 v49, 13, v49
	v_cmp_ne_u32_e32 vcc, v49, v79
	s_and_saveexec_b64 s[10:11], vcc
	s_cbranch_execz .LBB0_615
	v_add_u32_e32 v32, s0, v49
	v_mad_i64_i32 v[32:33], s[4:5], v32, s46, v[50:51]
	v_add_co_u32_e32 v34, vcc, 0x6000, v32
	v_mov_b32_e32 v79, v49
	s_nop 0
	v_addc_co_u32_e32 v35, vcc, 0, v33, vcc
	v_add_co_u32_e32 v32, vcc, 0x7000, v32
	s_nop 1
	v_addc_co_u32_e32 v33, vcc, 0, v33, vcc
	global_load_dwordx4 v[56:59], v[32:33], off
	global_load_dwordx4 v[68:71], v[32:33], off offset:1024
	global_load_dwordx4 v[80:83], v[32:33], off offset:2048
	global_load_dwordx4 v[84:87], v[32:33], off offset:3072
	global_load_dwordx4 v[44:47], v[34:35], off
	global_load_dwordx4 v[40:43], v[34:35], off offset:1024
	global_load_dwordx4 v[36:39], v[34:35], off offset:2048
	s_nop 0
	global_load_dwordx4 v[32:35], v[34:35], off offset:3072
	s_waitcnt vmcnt(7)
	v_pk_add_f32 v[66:67], v[56:57], 1.0 op_sel_hi:[1,0]
	v_pk_add_f32 v[64:65], v[58:59], 1.0 op_sel_hi:[1,0]
	s_waitcnt vmcnt(6)
	v_pk_add_f32 v[62:63], v[68:69], 1.0 op_sel_hi:[1,0]
	v_pk_add_f32 v[60:61], v[70:71], 1.0 op_sel_hi:[1,0]
	s_waitcnt vmcnt(5)
	v_pk_add_f32 v[58:59], v[80:81], 1.0 op_sel_hi:[1,0]
	v_pk_add_f32 v[56:57], v[82:83], 1.0 op_sel_hi:[1,0]
	s_waitcnt vmcnt(0)
	v_pk_add_f32 v[70:71], v[84:85], 1.0 op_sel_hi:[1,0]
	v_pk_add_f32 v[68:69], v[86:87], 1.0 op_sel_hi:[1,0]
	s_branch .LBB0_615
.LBB0_618:
	s_waitcnt vmcnt(0)
	s_or_b64 exec, exec, s[2:3]

.Lg4_r3_nl:
	s_waitcnt lgkmcnt(1)
	v_mfma_f32_16x16x32_f16 v[0:3], v[132:135], v[242:245], v[0:3]
	v_mfma_f32_16x16x32_f16 v[16:19], v[136:139], v[242:245], v[16:19]
	v_mfma_f32_16x16x32_f16 v[32:35], v[140:143], v[242:245], v[32:35]
	v_mfma_f32_16x16x32_f16 v[48:51], v[144:147], v[242:245], v[48:51]
	v_mfma_f32_16x16x32_f16 v[64:67], v[148:151], v[242:245], v[64:67]
	v_mfma_f32_16x16x32_f16 v[80:83], v[152:155], v[242:245], v[80:83]
	v_mfma_f32_16x16x32_f16 v[96:99], v[156:159], v[242:245], v[96:99]
	v_mfma_f32_16x16x32_f16 v[116:119], v[160:163], v[242:245], v[116:119]
	ds_read_b128 v[242:245], v223 offset:36864
	s_waitcnt lgkmcnt(1)
	v_mfma_f32_16x16x32_f16 v[4:7], v[132:135], v[112:115], v[4:7]
	v_mfma_f32_16x16x32_f16 v[20:23], v[136:139], v[112:115], v[20:23]
	v_mfma_f32_16x16x32_f16 v[36:39], v[140:143], v[112:115], v[36:39]
	v_mfma_f32_16x16x32_f16 v[52:55], v[144:147], v[112:115], v[52:55]
	v_mfma_f32_16x16x32_f16 v[68:71], v[148:151], v[112:115], v[68:71]
	v_mfma_f32_16x16x32_f16 v[84:87], v[152:155], v[112:115], v[84:87]
	v_mfma_f32_16x16x32_f16 v[100:103], v[156:159], v[112:115], v[100:103]
	v_mfma_f32_16x16x32_f16 v[120:123], v[160:163], v[112:115], v[120:123]
	ds_read_b128 v[112:115], v223 offset:38912
	s_waitcnt lgkmcnt(1)
	v_mfma_f32_16x16x32_f16 v[8:11], v[132:135], v[242:245], v[8:11]
	v_mfma_f32_16x16x32_f16 v[24:27], v[136:139], v[242:245], v[24:27]
	v_mfma_f32_16x16x32_f16 v[40:43], v[140:143], v[242:245], v[40:43]
	v_mfma_f32_16x16x32_f16 v[56:59], v[144:147], v[242:245], v[56:59]
	v_mfma_f32_16x16x32_f16 v[72:75], v[148:151], v[242:245], v[72:75]
	v_mfma_f32_16x16x32_f16 v[88:91], v[152:155], v[242:245], v[88:91]
	v_mfma_f32_16x16x32_f16 v[104:107], v[156:159], v[242:245], v[104:107]
	v_mfma_f32_16x16x32_f16 v[124:127], v[160:163], v[242:245], v[124:127]
	ds_read_b128 v[242:245], v233 offset:32768
	s_waitcnt lgkmcnt(1)
	v_mfma_f32_16x16x32_f16 v[12:15], v[132:135], v[112:115], v[12:15]
	v_mfma_f32_16x16x32_f16 v[28:31], v[136:139], v[112:115], v[28:31]
	v_mfma_f32_16x16x32_f16 v[44:47], v[140:143], v[112:115], v[44:47]
	v_mfma_f32_16x16x32_f16 v[60:63], v[144:147], v[112:115], v[60:63]
	v_mfma_f32_16x16x32_f16 v[76:79], v[148:151], v[112:115], v[76:79]
	v_mfma_f32_16x16x32_f16 v[92:95], v[152:155], v[112:115], v[92:95]
	v_mfma_f32_16x16x32_f16 v[108:111], v[156:159], v[112:115], v[108:111]
	v_mfma_f32_16x16x32_f16 v[128:131], v[160:163], v[112:115], v[128:131]
	ds_read_b128 v[112:115], v233 offset:34816
	s_waitcnt lgkmcnt(1)
	v_mfma_f32_16x16x32_f16 v[0:3], v[164:167], v[242:245], v[0:3]
	v_mfma_f32_16x16x32_f16 v[16:19], v[168:171], v[242:245], v[16:19]
	v_mfma_f32_16x16x32_f16 v[32:35], v[172:175], v[242:245], v[32:35]
	v_mfma_f32_16x16x32_f16 v[48:51], v[176:179], v[242:245], v[48:51]
	v_mfma_f32_16x16x32_f16 v[64:67], v[224:227], v[242:245], v[64:67]
	v_mfma_f32_16x16x32_f16 v[80:83], v[228:231], v[242:245], v[80:83]
	v_mfma_f32_16x16x32_f16 v[96:99], v[234:237], v[242:245], v[96:99]
	v_mfma_f32_16x16x32_f16 v[116:119], v[238:241], v[242:245], v[116:119]
	ds_read_b128 v[242:245], v233 offset:36864
	s_waitcnt lgkmcnt(1)
	v_mfma_f32_16x16x32_f16 v[4:7], v[164:167], v[112:115], v[4:7]
	v_mfma_f32_16x16x32_f16 v[20:23], v[168:171], v[112:115], v[20:23]
	v_mfma_f32_16x16x32_f16 v[36:39], v[172:175], v[112:115], v[36:39]
	v_mfma_f32_16x16x32_f16 v[52:55], v[176:179], v[112:115], v[52:55]
	v_mfma_f32_16x16x32_f16 v[68:71], v[224:227], v[112:115], v[68:71]
	v_mfma_f32_16x16x32_f16 v[84:87], v[228:231], v[112:115], v[84:87]
	v_mfma_f32_16x16x32_f16 v[100:103], v[234:237], v[112:115], v[100:103]
	v_mfma_f32_16x16x32_f16 v[120:123], v[238:241], v[112:115], v[120:123]
	ds_read_b128 v[112:115], v233 offset:38912
	s_waitcnt lgkmcnt(1)
	v_mfma_f32_16x16x32_f16 v[8:11], v[164:167], v[242:245], v[8:11]
	v_mfma_f32_16x16x32_f16 v[24:27], v[168:171], v[242:245], v[24:27]
	v_mfma_f32_16x16x32_f16 v[40:43], v[172:175], v[242:245], v[40:43]
	v_mfma_f32_16x16x32_f16 v[56:59], v[176:179], v[242:245], v[56:59]
	v_mfma_f32_16x16x32_f16 v[72:75], v[224:227], v[242:245], v[72:75]
	v_mfma_f32_16x16x32_f16 v[88:91], v[228:231], v[242:245], v[88:91]
	v_mfma_f32_16x16x32_f16 v[104:107], v[234:237], v[242:245], v[104:107]
	v_mfma_f32_16x16x32_f16 v[124:127], v[238:241], v[242:245], v[124:127]
	s_waitcnt lgkmcnt(0)
	v_mfma_f32_16x16x32_f16 v[12:15], v[164:167], v[112:115], v[12:15]
	v_mfma_f32_16x16x32_f16 v[28:31], v[168:171], v[112:115], v[28:31]
	v_mfma_f32_16x16x32_f16 v[44:47], v[172:175], v[112:115], v[44:47]
	v_mfma_f32_16x16x32_f16 v[60:63], v[176:179], v[112:115], v[60:63]
	v_mfma_f32_16x16x32_f16 v[76:79], v[224:227], v[112:115], v[76:79]
	v_mfma_f32_16x16x32_f16 v[92:95], v[228:231], v[112:115], v[92:95]
	v_mfma_f32_16x16x32_f16 v[108:111], v[234:237], v[112:115], v[108:111]
	v_mfma_f32_16x16x32_f16 v[128:131], v[238:241], v[112:115], v[128:131]
	v_xor_b32_e32 v223, 0x4000, v223
	v_xor_b32_e32 v233, 0x4000, v233
	s_sub_u32 s16, s16, 1
	s_cmp_lg_u32 s16, -1
	s_cbranch_scc1 .Lg4_r3
	s_nop 7
	v_bfe_u32 v208, v182, 7, 1
	v_bfe_u32 v223, v182, 4, 2
	v_lshlrev_b32_e32 v223, 2, v223
	v_lshl_or_b32 v208, v208, 7, v223
	v_add_u32_e32 v180, s0, v208
	v_bfe_u32 v208, v182, 6, 1
	v_and_b32_e32 v223, 15, v182
	v_lshl_or_b32 v208, v208, 6, v223
	v_add_u32_e32 v208, s14, v208
	v_lshlrev_b32_e32 v181, 2, v208
	s_lshr_b32 s4, s0, 13
	s_add_i32 s4, s4, s10
	s_mul_hi_i32 s9, s4, 0x9000
	s_mul_i32 s8, s4, 0x9000
	s_add_u32 s8, s50, s8
	s_addc_u32 s9, s51, s9
	s_add_u32 s8, s8, 0x8000
	s_addc_u32 s9, s9, 0
	v_mov_b32_e32 v247, s9
	v_add_co_u32_e32 v246, vcc, s8, v181
	s_nop 1
	v_addc_co_u32_e32 v247, vcc, 0, v247, vcc
	v_lshl_add_u32 v164, v180, 12, v181
	v_add_u32_e32 v165, 0x1000, v164
	v_add_u32_e32 v166, 0x3000, v164
	v_add_u32_e32 v167, 0x11000, v164
	v_add_u32_e32 v168, 0x13000, v164
	v_add_u32_e32 v169, 0x21000, v164
	v_add_u32_e32 v170, 0x23000, v164
	v_add_u32_e32 v171, 0x31000, v164
	v_add_u32_e32 v172, 0x33000, v164
	v_lshlrev_b32_e32 v115, 3, v180
	v_add_u32_e32 v115, 0x1e200000, v115
	v_mov_b32_e32 v223, s71
	v_mul_u32_u24_e32 v223, 3, v223
	v_add_u32_e32 v223, 1, v223
	v_lshl_add_u32 v208, v223, 12, v181
	global_load_dwordx2 v[132:133], v115, s[30:31] offset:0
	global_load_dwordx2 v[134:135], v115, s[30:31] offset:8
	global_load_dwordx2 v[136:137], v115, s[30:31] offset:16
	global_load_dwordx2 v[138:139], v115, s[30:31] offset:24
	global_load_dwordx2 v[140:141], v115, s[30:31] offset:128
	global_load_dwordx2 v[142:143], v115, s[30:31] offset:136
	global_load_dwordx2 v[144:145], v115, s[30:31] offset:144
	global_load_dwordx2 v[146:147], v115, s[30:31] offset:152
	global_load_dwordx2 v[148:149], v115, s[30:31] offset:256
	global_load_dwordx2 v[150:151], v115, s[30:31] offset:264
	global_load_dwordx2 v[152:153], v115, s[30:31] offset:272
	global_load_dwordx2 v[154:155], v115, s[30:31] offset:280
	global_load_dwordx2 v[156:157], v115, s[30:31] offset:384
	global_load_dwordx2 v[158:159], v115, s[30:31] offset:392
	global_load_dwordx2 v[160:161], v115, s[30:31] offset:400
	global_load_dwordx2 v[162:163], v115, s[30:31] offset:408
	global_load_dword v239, v208, s[24:25] offset:0
	global_load_dword v243, v208, s[26:27] offset:0
	global_load_dword v240, v208, s[24:25] offset:64
	global_load_dword v244, v208, s[26:27] offset:64
	global_load_dword v241, v208, s[24:25] offset:128
	global_load_dword v245, v208, s[26:27] offset:128
	global_load_dword v242, v208, s[24:25] offset:192
	global_load_dword v112, v208, s[26:27] offset:192
	global_load_dword v173, v[246:247], off offset:0
	global_load_dword v174, v[246:247], off offset:64
	global_load_dword v175, v[246:247], off offset:128
	global_load_dword v176, v[246:247], off offset:192
	global_load_dword v177, v165, s[28:29] offset:-4096
	global_load_dword v178, v165, s[28:29] offset:0
	global_load_dword v179, v166, s[28:29] offset:-4096
	global_load_dword v224, v166, s[28:29] offset:0
	global_load_dword v225, v167, s[28:29] offset:-4096
	global_load_dword v226, v167, s[28:29] offset:0
	global_load_dword v227, v168, s[28:29] offset:-4096
	global_load_dword v228, v168, s[28:29] offset:0
	global_load_dword v229, v169, s[28:29] offset:-4096
	global_load_dword v230, v169, s[28:29] offset:0
	global_load_dword v231, v170, s[28:29] offset:-4096
	global_load_dword v234, v170, s[28:29] offset:0
	global_load_dword v235, v171, s[28:29] offset:-4096
	global_load_dword v236, v171, s[28:29] offset:0
	global_load_dword v237, v172, s[28:29] offset:-4096
	global_load_dword v238, v172, s[28:29] offset:0
	s_waitcnt vmcnt(15)
	v_add_f32_e32 v173, 1.0, v173
	v_add_f32_e32 v174, 1.0, v174
	v_add_f32_e32 v175, 1.0, v175
	v_add_f32_e32 v176, 1.0, v176
	v_mul_f32_e32 v173, 0.5, v173
	v_mul_f32_e32 v174, 0.5, v174
	v_mul_f32_e32 v175, 0.5, v175
	v_mul_f32_e32 v176, 0.5, v176
	v_sub_f32_e32 v177, v177, v132
	v_mul_f32_e32 v177, v177, v133
	v_fma_f32 v177, v239, v177, v243
	v_mul_f32_e32 v0, v0, v173
	v_fmac_f32_e32 v0, 0x3fb504f3, v177
	global_load_dword v177, v165, s[28:29] offset:-4032
	global_store_dword v165, v0, s[28:29] offset:-4096
	s_waitcnt vmcnt(16)
	v_sub_f32_e32 v178, v178, v134
	v_mul_f32_e32 v178, v178, v135
	v_fma_f32 v178, v239, v178, v243
	v_mul_f32_e32 v1, v1, v173
	v_fmac_f32_e32 v1, 0x3fb504f3, v178
	global_load_dword v178, v165, s[28:29] offset:64
	global_store_dword v165, v1, s[28:29] offset:0
	s_waitcnt vmcnt(17)
	v_sub_f32_e32 v179, v179, v136
	v_mul_f32_e32 v179, v179, v137
	v_fma_f32 v179, v239, v179, v243
	v_mul_f32_e32 v2, v2, v173
	v_fmac_f32_e32 v2, 0x3fb504f3, v179
	global_load_dword v179, v166, s[28:29] offset:-4032
	global_store_dword v166, v2, s[28:29] offset:-4096
	s_waitcnt vmcnt(18)
	v_sub_f32_e32 v224, v224, v138
	v_mul_f32_e32 v224, v224, v139
	v_fma_f32 v224, v239, v224, v243
	v_mul_f32_e32 v3, v3, v173
	v_fmac_f32_e32 v3, 0x3fb504f3, v224
	global_load_dword v224, v166, s[28:29] offset:64
	global_store_dword v166, v3, s[28:29] offset:0
	s_waitcnt vmcnt(19)
	v_sub_f32_e32 v225, v225, v140
	v_mul_f32_e32 v225, v225, v141
	v_fma_f32 v225, v239, v225, v243
	v_mul_f32_e32 v16, v16, v173
	v_fmac_f32_e32 v16, 0x3fb504f3, v225
	global_load_dword v225, v167, s[28:29] offset:-4032
	global_store_dword v167, v16, s[28:29] offset:-4096
	s_waitcnt vmcnt(20)
	v_sub_f32_e32 v226, v226, v142
	v_mul_f32_e32 v226, v226, v143
	v_fma_f32 v226, v239, v226, v243
	v_mul_f32_e32 v17, v17, v173
	v_fmac_f32_e32 v17, 0x3fb504f3, v226
	global_load_dword v226, v167, s[28:29] offset:64
	global_store_dword v167, v17, s[28:29] offset:0
	s_waitcnt vmcnt(21)
	v_sub_f32_e32 v227, v227, v144
	v_mul_f32_e32 v227, v227, v145
	v_fma_f32 v227, v239, v227, v243
	v_mul_f32_e32 v18, v18, v173
	v_fmac_f32_e32 v18, 0x3fb504f3, v227
	global_load_dword v227, v168, s[28:29] offset:-4032
	global_store_dword v168, v18, s[28:29] offset:-4096
	s_waitcnt vmcnt(22)
	v_sub_f32_e32 v228, v228, v146
	v_mul_f32_e32 v228, v228, v147
	v_fma_f32 v228, v239, v228, v243
	v_mul_f32_e32 v19, v19, v173
	v_fmac_f32_e32 v19, 0x3fb504f3, v228
	global_load_dword v228, v168, s[28:29] offset:64
	global_store_dword v168, v19, s[28:29] offset:0
	s_waitcnt vmcnt(23)
	v_sub_f32_e32 v229, v229, v148
	v_mul_f32_e32 v229, v229, v149
	v_fma_f32 v229, v239, v229, v243
	v_mul_f32_e32 v32, v32, v173
	v_fmac_f32_e32 v32, 0x3fb504f3, v229
	global_load_dword v229, v169, s[28:29] offset:-4032
	global_store_dword v169, v32, s[28:29] offset:-4096
	s_waitcnt vmcnt(24)
	v_sub_f32_e32 v230, v230, v150
	v_mul_f32_e32 v230, v230, v151
	v_fma_f32 v230, v239, v230, v243
	v_mul_f32_e32 v33, v33, v173
	v_fmac_f32_e32 v33, 0x3fb504f3, v230
	global_load_dword v230, v169, s[28:29] offset:64
	global_store_dword v169, v33, s[28:29] offset:0
	s_waitcnt vmcnt(25)
	v_sub_f32_e32 v231, v231, v152
	v_mul_f32_e32 v231, v231, v153
	v_fma_f32 v231, v239, v231, v243
	v_mul_f32_e32 v34, v34, v173
	v_fmac_f32_e32 v34, 0x3fb504f3, v231
	global_load_dword v231, v170, s[28:29] offset:-4032
	global_store_dword v170, v34, s[28:29] offset:-4096
	s_waitcnt vmcnt(26)
	v_sub_f32_e32 v234, v234, v154
	v_mul_f32_e32 v234, v234, v155
	v_fma_f32 v234, v239, v234, v243
	v_mul_f32_e32 v35, v35, v173
	v_fmac_f32_e32 v35, 0x3fb504f3, v234
	global_load_dword v234, v170, s[28:29] offset:64
	global_store_dword v170, v35, s[28:29] offset:0
	s_waitcnt vmcnt(27)
	v_sub_f32_e32 v235, v235, v156
	v_mul_f32_e32 v235, v235, v157
	v_fma_f32 v235, v239, v235, v243
	v_mul_f32_e32 v48, v48, v173
	v_fmac_f32_e32 v48, 0x3fb504f3, v235
	global_load_dword v235, v171, s[28:29] offset:-4032
	global_store_dword v171, v48, s[28:29] offset:-4096
	s_waitcnt vmcnt(28)
	v_sub_f32_e32 v236, v236, v158
	v_mul_f32_e32 v236, v236, v159
	v_fma_f32 v236, v239, v236, v243
	v_mul_f32_e32 v49, v49, v173
	v_fmac_f32_e32 v49, 0x3fb504f3, v236
	global_load_dword v236, v171, s[28:29] offset:64
	global_store_dword v171, v49, s[28:29] offset:0
	s_waitcnt vmcnt(29)
	v_sub_f32_e32 v237, v237, v160
	v_mul_f32_e32 v237, v237, v161
	v_fma_f32 v237, v239, v237, v243
	v_mul_f32_e32 v50, v50, v173
	v_fmac_f32_e32 v50, 0x3fb504f3, v237
	global_load_dword v237, v172, s[28:29] offset:-4032
	global_store_dword v172, v50, s[28:29] offset:-4096
	s_waitcnt vmcnt(30)
	v_sub_f32_e32 v238, v238, v162
	v_mul_f32_e32 v238, v238, v163
	v_fma_f32 v238, v239, v238, v243
	v_mul_f32_e32 v51, v51, v173
	v_fmac_f32_e32 v51, 0x3fb504f3, v238
	global_load_dword v238, v172, s[28:29] offset:64
	global_store_dword v172, v51, s[28:29] offset:0
	s_waitcnt vmcnt(31)
	v_sub_f32_e32 v177, v177, v132
	v_mul_f32_e32 v177, v177, v133
	v_fma_f32 v177, v240, v177, v244
	v_mul_f32_e32 v4, v4, v174
	v_fmac_f32_e32 v4, 0x3fb504f3, v177
	global_load_dword v177, v165, s[28:29] offset:-3968
	global_store_dword v165, v4, s[28:29] offset:-4032
	s_waitcnt vmcnt(31)
	v_sub_f32_e32 v178, v178, v134
	v_mul_f32_e32 v178, v178, v135
	v_fma_f32 v178, v240, v178, v244
	v_mul_f32_e32 v5, v5, v174
	v_fmac_f32_e32 v5, 0x3fb504f3, v178
	global_load_dword v178, v165, s[28:29] offset:128
	global_store_dword v165, v5, s[28:29] offset:64
	s_waitcnt vmcnt(31)
	v_sub_f32_e32 v179, v179, v136
	v_mul_f32_e32 v179, v179, v137
	v_fma_f32 v179, v240, v179, v244
	v_mul_f32_e32 v6, v6, v174
	v_fmac_f32_e32 v6, 0x3fb504f3, v179
	global_load_dword v179, v166, s[28:29] offset:-3968
	global_store_dword v166, v6, s[28:29] offset:-4032
	s_waitcnt vmcnt(31)
	v_sub_f32_e32 v224, v224, v138
	v_mul_f32_e32 v224, v224, v139
	v_fma_f32 v224, v240, v224, v244
	v_mul_f32_e32 v7, v7, v174
	v_fmac_f32_e32 v7, 0x3fb504f3, v224
	global_load_dword v224, v166, s[28:29] offset:128
	global_store_dword v166, v7, s[28:29] offset:64
	s_waitcnt vmcnt(31)
	v_sub_f32_e32 v225, v225, v140
	v_mul_f32_e32 v225, v225, v141
	v_fma_f32 v225, v240, v225, v244
	v_mul_f32_e32 v20, v20, v174
	v_fmac_f32_e32 v20, 0x3fb504f3, v225
	global_load_dword v225, v167, s[28:29] offset:-3968
	global_store_dword v167, v20, s[28:29] offset:-4032
	s_waitcnt vmcnt(31)
	v_sub_f32_e32 v226, v226, v142
	v_mul_f32_e32 v226, v226, v143
	v_fma_f32 v226, v240, v226, v244
	v_mul_f32_e32 v21, v21, v174
	v_fmac_f32_e32 v21, 0x3fb504f3, v226
	global_load_dword v226, v167, s[28:29] offset:128
	global_store_dword v167, v21, s[28:29] offset:64
	s_waitcnt vmcnt(31)
	v_sub_f32_e32 v227, v227, v144
	v_mul_f32_e32 v227, v227, v145
	v_fma_f32 v227, v240, v227, v244
	v_mul_f32_e32 v22, v22, v174
	v_fmac_f32_e32 v22, 0x3fb504f3, v227
	global_load_dword v227, v168, s[28:29] offset:-3968
	global_store_dword v168, v22, s[28:29] offset:-4032
	s_waitcnt vmcnt(31)
	v_sub_f32_e32 v228, v228, v146
	v_mul_f32_e32 v228, v228, v147
	v_fma_f32 v228, v240, v228, v244
	v_mul_f32_e32 v23, v23, v174
	v_fmac_f32_e32 v23, 0x3fb504f3, v228
	global_load_dword v228, v168, s[28:29] offset:128
	global_store_dword v168, v23, s[28:29] offset:64
	s_waitcnt vmcnt(31)
	v_sub_f32_e32 v229, v229, v148
	v_mul_f32_e32 v229, v229, v149
	v_fma_f32 v229, v240, v229, v244
	v_mul_f32_e32 v36, v36, v174
	v_fmac_f32_e32 v36, 0x3fb504f3, v229
	global_load_dword v229, v169, s[28:29] offset:-3968
	global_store_dword v169, v36, s[28:29] offset:-4032
	s_waitcnt vmcnt(31)
	v_sub_f32_e32 v230, v230, v150
	v_mul_f32_e32 v230, v230, v151
	v_fma_f32 v230, v240, v230, v244
	v_mul_f32_e32 v37, v37, v174
	v_fmac_f32_e32 v37, 0x3fb504f3, v230
	global_load_dword v230, v169, s[28:29] offset:128
	global_store_dword v169, v37, s[28:29] offset:64
	s_waitcnt vmcnt(31)
	v_sub_f32_e32 v231, v231, v152
	v_mul_f32_e32 v231, v231, v153
	v_fma_f32 v231, v240, v231, v244
	v_mul_f32_e32 v38, v38, v174
	v_fmac_f32_e32 v38, 0x3fb504f3, v231
	global_load_dword v231, v170, s[28:29] offset:-3968
	global_store_dword v170, v38, s[28:29] offset:-4032
	s_waitcnt vmcnt(31)
	v_sub_f32_e32 v234, v234, v154
	v_mul_f32_e32 v234, v234, v155
	v_fma_f32 v234, v240, v234, v244
	v_mul_f32_e32 v39, v39, v174
	v_fmac_f32_e32 v39, 0x3fb504f3, v234
	global_load_dword v234, v170, s[28:29] offset:128
	global_store_dword v170, v39, s[28:29] offset:64
	s_waitcnt vmcnt(31)
	v_sub_f32_e32 v235, v235, v156
	v_mul_f32_e32 v235, v235, v157
	v_fma_f32 v235, v240, v235, v244
	v_mul_f32_e32 v52, v52, v174
	v_fmac_f32_e32 v52, 0x3fb504f3, v235
	global_load_dword v235, v171, s[28:29] offset:-3968
	global_store_dword v171, v52, s[28:29] offset:-4032
	s_waitcnt vmcnt(31)
	v_sub_f32_e32 v236, v236, v158
	v_mul_f32_e32 v236, v236, v159
	v_fma_f32 v236, v240, v236, v244
	v_mul_f32_e32 v53, v53, v174
	v_fmac_f32_e32 v53, 0x3fb504f3, v236
	global_load_dword v236, v171, s[28:29] offset:128
	global_store_dword v171, v53, s[28:29] offset:64
	s_waitcnt vmcnt(31)
	v_sub_f32_e32 v237, v237, v160
	v_mul_f32_e32 v237, v237, v161
	v_fma_f32 v237, v240, v237, v244
	v_mul_f32_e32 v54, v54, v174
	v_fmac_f32_e32 v54, 0x3fb504f3, v237
	global_load_dword v237, v172, s[28:29] offset:-3968
	global_store_dword v172, v54, s[28:29] offset:-4032
	s_waitcnt vmcnt(31)
	v_sub_f32_e32 v238, v238, v162
	v_mul_f32_e32 v238, v238, v163
	v_fma_f32 v238, v240, v238, v244
	v_mul_f32_e32 v55, v55, v174
	v_fmac_f32_e32 v55, 0x3fb504f3, v238
	global_load_dword v238, v172, s[28:29] offset:128
	global_store_dword v172, v55, s[28:29] offset:64
	s_waitcnt vmcnt(31)
	v_sub_f32_e32 v177, v177, v132
	v_mul_f32_e32 v177, v177, v133
	v_fma_f32 v177, v241, v177, v245
	v_mul_f32_e32 v8, v8, v175
	v_fmac_f32_e32 v8, 0x3fb504f3, v177
	global_load_dword v177, v165, s[28:29] offset:-3904
	global_store_dword v165, v8, s[28:29] offset:-3968
	s_waitcnt vmcnt(31)
	v_sub_f32_e32 v178, v178, v134
	v_mul_f32_e32 v178, v178, v135
	v_fma_f32 v178, v241, v178, v245
	v_mul_f32_e32 v9, v9, v175
	v_fmac_f32_e32 v9, 0x3fb504f3, v178
	global_load_dword v178, v165, s[28:29] offset:192
	global_store_dword v165, v9, s[28:29] offset:128
	s_waitcnt vmcnt(31)
	v_sub_f32_e32 v179, v179, v136
	v_mul_f32_e32 v179, v179, v137
	v_fma_f32 v179, v241, v179, v245
	v_mul_f32_e32 v10, v10, v175
	v_fmac_f32_e32 v10, 0x3fb504f3, v179
	global_load_dword v179, v166, s[28:29] offset:-3904
	global_store_dword v166, v10, s[28:29] offset:-3968
	s_waitcnt vmcnt(31)
	v_sub_f32_e32 v224, v224, v138
	v_mul_f32_e32 v224, v224, v139
	v_fma_f32 v224, v241, v224, v245
	v_mul_f32_e32 v11, v11, v175
	v_fmac_f32_e32 v11, 0x3fb504f3, v224
	global_load_dword v224, v166, s[28:29] offset:192
	global_store_dword v166, v11, s[28:29] offset:128
	s_waitcnt vmcnt(31)
	v_sub_f32_e32 v225, v225, v140
	v_mul_f32_e32 v225, v225, v141
	v_fma_f32 v225, v241, v225, v245
	v_mul_f32_e32 v24, v24, v175
	v_fmac_f32_e32 v24, 0x3fb504f3, v225
	global_load_dword v225, v167, s[28:29] offset:-3904
	global_store_dword v167, v24, s[28:29] offset:-3968
	s_waitcnt vmcnt(31)
	v_sub_f32_e32 v226, v226, v142
	v_mul_f32_e32 v226, v226, v143
	v_fma_f32 v226, v241, v226, v245
	v_mul_f32_e32 v25, v25, v175
	v_fmac_f32_e32 v25, 0x3fb504f3, v226
	global_load_dword v226, v167, s[28:29] offset:192
	global_store_dword v167, v25, s[28:29] offset:128
	s_waitcnt vmcnt(31)
	v_sub_f32_e32 v227, v227, v144
	v_mul_f32_e32 v227, v227, v145
	v_fma_f32 v227, v241, v227, v245
	v_mul_f32_e32 v26, v26, v175
	v_fmac_f32_e32 v26, 0x3fb504f3, v227
	global_load_dword v227, v168, s[28:29] offset:-3904
	global_store_dword v168, v26, s[28:29] offset:-3968
	s_waitcnt vmcnt(31)
	v_sub_f32_e32 v228, v228, v146
	v_mul_f32_e32 v228, v228, v147
	v_fma_f32 v228, v241, v228, v245
	v_mul_f32_e32 v27, v27, v175
	v_fmac_f32_e32 v27, 0x3fb504f3, v228
	global_load_dword v228, v168, s[28:29] offset:192
	global_store_dword v168, v27, s[28:29] offset:128
	s_waitcnt vmcnt(31)
	v_sub_f32_e32 v229, v229, v148
	v_mul_f32_e32 v229, v229, v149
	v_fma_f32 v229, v241, v229, v245
	v_mul_f32_e32 v40, v40, v175
	v_fmac_f32_e32 v40, 0x3fb504f3, v229
	global_load_dword v229, v169, s[28:29] offset:-3904
	global_store_dword v169, v40, s[28:29] offset:-3968
	s_waitcnt vmcnt(31)
	v_sub_f32_e32 v230, v230, v150
	v_mul_f32_e32 v230, v230, v151
	v_fma_f32 v230, v241, v230, v245
	v_mul_f32_e32 v41, v41, v175
	v_fmac_f32_e32 v41, 0x3fb504f3, v230
	global_load_dword v230, v169, s[28:29] offset:192
	global_store_dword v169, v41, s[28:29] offset:128
	s_waitcnt vmcnt(31)
	v_sub_f32_e32 v231, v231, v152
	v_mul_f32_e32 v231, v231, v153
	v_fma_f32 v231, v241, v231, v245
	v_mul_f32_e32 v42, v42, v175
	v_fmac_f32_e32 v42, 0x3fb504f3, v231
	global_load_dword v231, v170, s[28:29] offset:-3904
	global_store_dword v170, v42, s[28:29] offset:-3968
	s_waitcnt vmcnt(31)
	v_sub_f32_e32 v234, v234, v154
	v_mul_f32_e32 v234, v234, v155
	v_fma_f32 v234, v241, v234, v245
	v_mul_f32_e32 v43, v43, v175
	v_fmac_f32_e32 v43, 0x3fb504f3, v234
	global_load_dword v234, v170, s[28:29] offset:192
	global_store_dword v170, v43, s[28:29] offset:128
	s_waitcnt vmcnt(31)
	v_sub_f32_e32 v235, v235, v156
	v_mul_f32_e32 v235, v235, v157
	v_fma_f32 v235, v241, v235, v245
	v_mul_f32_e32 v56, v56, v175
	v_fmac_f32_e32 v56, 0x3fb504f3, v235
	global_load_dword v235, v171, s[28:29] offset:-3904
	global_store_dword v171, v56, s[28:29] offset:-3968
	s_waitcnt vmcnt(31)
	v_sub_f32_e32 v236, v236, v158
	v_mul_f32_e32 v236, v236, v159
	v_fma_f32 v236, v241, v236, v245
	v_mul_f32_e32 v57, v57, v175
	v_fmac_f32_e32 v57, 0x3fb504f3, v236
	global_load_dword v236, v171, s[28:29] offset:192
	global_store_dword v171, v57, s[28:29] offset:128
	s_waitcnt vmcnt(31)
	v_sub_f32_e32 v237, v237, v160
	v_mul_f32_e32 v237, v237, v161
	v_fma_f32 v237, v241, v237, v245
	v_mul_f32_e32 v58, v58, v175
	v_fmac_f32_e32 v58, 0x3fb504f3, v237
	global_load_dword v237, v172, s[28:29] offset:-3904
	global_store_dword v172, v58, s[28:29] offset:-3968
	s_waitcnt vmcnt(31)
	v_sub_f32_e32 v238, v238, v162
	v_mul_f32_e32 v238, v238, v163
	v_fma_f32 v238, v241, v238, v245
	v_mul_f32_e32 v59, v59, v175
	v_fmac_f32_e32 v59, 0x3fb504f3, v238
	global_load_dword v238, v172, s[28:29] offset:192
	global_store_dword v172, v59, s[28:29] offset:128
	s_waitcnt vmcnt(31)
	v_sub_f32_e32 v177, v177, v132
	v_mul_f32_e32 v177, v177, v133
	v_fma_f32 v177, v242, v177, v112
	v_mul_f32_e32 v12, v12, v176
	v_fmac_f32_e32 v12, 0x3fb504f3, v177
	global_store_dword v165, v12, s[28:29] offset:-3904
	s_waitcnt vmcnt(30)
	v_sub_f32_e32 v178, v178, v134
	v_mul_f32_e32 v178, v178, v135
	v_fma_f32 v178, v242, v178, v112
	v_mul_f32_e32 v13, v13, v176
	v_fmac_f32_e32 v13, 0x3fb504f3, v178
	global_store_dword v165, v13, s[28:29] offset:192
	s_waitcnt vmcnt(29)
	v_sub_f32_e32 v179, v179, v136
	v_mul_f32_e32 v179, v179, v137
	v_fma_f32 v179, v242, v179, v112
	v_mul_f32_e32 v14, v14, v176
	v_fmac_f32_e32 v14, 0x3fb504f3, v179
	global_store_dword v166, v14, s[28:29] offset:-3904
	s_waitcnt vmcnt(28)
	v_sub_f32_e32 v224, v224, v138
	v_mul_f32_e32 v224, v224, v139
	v_fma_f32 v224, v242, v224, v112
	v_mul_f32_e32 v15, v15, v176
	v_fmac_f32_e32 v15, 0x3fb504f3, v224
	global_store_dword v166, v15, s[28:29] offset:192
	s_waitcnt vmcnt(27)
	v_sub_f32_e32 v225, v225, v140
	v_mul_f32_e32 v225, v225, v141
	v_fma_f32 v225, v242, v225, v112
	v_mul_f32_e32 v28, v28, v176
	v_fmac_f32_e32 v28, 0x3fb504f3, v225
	global_store_dword v167, v28, s[28:29] offset:-3904
	s_waitcnt vmcnt(26)
	v_sub_f32_e32 v226, v226, v142
	v_mul_f32_e32 v226, v226, v143
	v_fma_f32 v226, v242, v226, v112
	v_mul_f32_e32 v29, v29, v176
	v_fmac_f32_e32 v29, 0x3fb504f3, v226
	global_store_dword v167, v29, s[28:29] offset:192
	s_waitcnt vmcnt(25)
	v_sub_f32_e32 v227, v227, v144
	v_mul_f32_e32 v227, v227, v145
	v_fma_f32 v227, v242, v227, v112
	v_mul_f32_e32 v30, v30, v176
	v_fmac_f32_e32 v30, 0x3fb504f3, v227
	global_store_dword v168, v30, s[28:29] offset:-3904
	s_waitcnt vmcnt(24)
	v_sub_f32_e32 v228, v228, v146
	v_mul_f32_e32 v228, v228, v147
	v_fma_f32 v228, v242, v228, v112
	v_mul_f32_e32 v31, v31, v176
	v_fmac_f32_e32 v31, 0x3fb504f3, v228
	global_store_dword v168, v31, s[28:29] offset:192
	s_waitcnt vmcnt(23)
	v_sub_f32_e32 v229, v229, v148
	v_mul_f32_e32 v229, v229, v149
	v_fma_f32 v229, v242, v229, v112
	v_mul_f32_e32 v44, v44, v176
	v_fmac_f32_e32 v44, 0x3fb504f3, v229
	global_store_dword v169, v44, s[28:29] offset:-3904
	s_waitcnt vmcnt(22)
	v_sub_f32_e32 v230, v230, v150
	v_mul_f32_e32 v230, v230, v151
	v_fma_f32 v230, v242, v230, v112
	v_mul_f32_e32 v45, v45, v176
	v_fmac_f32_e32 v45, 0x3fb504f3, v230
	global_store_dword v169, v45, s[28:29] offset:192
	s_waitcnt vmcnt(21)
	v_sub_f32_e32 v231, v231, v152
	v_mul_f32_e32 v231, v231, v153
	v_fma_f32 v231, v242, v231, v112
	v_mul_f32_e32 v46, v46, v176
	v_fmac_f32_e32 v46, 0x3fb504f3, v231
	global_store_dword v170, v46, s[28:29] offset:-3904
	s_waitcnt vmcnt(20)
	v_sub_f32_e32 v234, v234, v154
	v_mul_f32_e32 v234, v234, v155
	v_fma_f32 v234, v242, v234, v112
	v_mul_f32_e32 v47, v47, v176
	v_fmac_f32_e32 v47, 0x3fb504f3, v234
	global_store_dword v170, v47, s[28:29] offset:192
	s_waitcnt vmcnt(19)
	v_sub_f32_e32 v235, v235, v156
	v_mul_f32_e32 v235, v235, v157
	v_fma_f32 v235, v242, v235, v112
	v_mul_f32_e32 v60, v60, v176
	v_fmac_f32_e32 v60, 0x3fb504f3, v235
	global_store_dword v171, v60, s[28:29] offset:-3904
	s_waitcnt vmcnt(18)
	v_sub_f32_e32 v236, v236, v158
	v_mul_f32_e32 v236, v236, v159
	v_fma_f32 v236, v242, v236, v112
	v_mul_f32_e32 v61, v61, v176
	v_fmac_f32_e32 v61, 0x3fb504f3, v236
	global_store_dword v171, v61, s[28:29] offset:192
	s_waitcnt vmcnt(17)
	v_sub_f32_e32 v237, v237, v160
	v_mul_f32_e32 v237, v237, v161
	v_fma_f32 v237, v242, v237, v112
	v_mul_f32_e32 v62, v62, v176
	v_fmac_f32_e32 v62, 0x3fb504f3, v237
	global_store_dword v172, v62, s[28:29] offset:-3904
	s_waitcnt vmcnt(16)
	v_sub_f32_e32 v238, v238, v162
	v_mul_f32_e32 v238, v238, v163
	v_fma_f32 v238, v242, v238, v112
	v_mul_f32_e32 v63, v63, v176
	v_fmac_f32_e32 v63, 0x3fb504f3, v238
	global_store_dword v172, v63, s[28:29] offset:192
	v_add_u32_e32 v180, 64, v180
	v_lshl_add_u32 v164, v180, 12, v181
	v_add_u32_e32 v165, 0x1000, v164
	v_add_u32_e32 v166, 0x3000, v164
	v_add_u32_e32 v167, 0x11000, v164
	v_add_u32_e32 v168, 0x13000, v164
	v_add_u32_e32 v169, 0x21000, v164
	v_add_u32_e32 v170, 0x23000, v164
	v_add_u32_e32 v171, 0x31000, v164
	v_add_u32_e32 v172, 0x33000, v164
	v_lshlrev_b32_e32 v35, 3, v180
	v_add_u32_e32 v35, 0x1e200000, v35
	v_mov_b32_e32 v49, s71
	v_mul_u32_u24_e32 v49, 3, v49
	v_add_u32_e32 v49, 1, v49
	v_lshl_add_u32 v48, v49, 12, v181
	global_load_dwordx2 v[132:133], v35, s[30:31] offset:0
	global_load_dwordx2 v[134:135], v35, s[30:31] offset:8
	global_load_dwordx2 v[136:137], v35, s[30:31] offset:16
	global_load_dwordx2 v[138:139], v35, s[30:31] offset:24
	global_load_dwordx2 v[140:141], v35, s[30:31] offset:128
	global_load_dwordx2 v[142:143], v35, s[30:31] offset:136
	global_load_dwordx2 v[144:145], v35, s[30:31] offset:144
	global_load_dwordx2 v[146:147], v35, s[30:31] offset:152
	global_load_dwordx2 v[148:149], v35, s[30:31] offset:256
	global_load_dwordx2 v[150:151], v35, s[30:31] offset:264
	global_load_dwordx2 v[152:153], v35, s[30:31] offset:272
	global_load_dwordx2 v[154:155], v35, s[30:31] offset:280
	global_load_dwordx2 v[156:157], v35, s[30:31] offset:384
	global_load_dwordx2 v[158:159], v35, s[30:31] offset:392
	global_load_dwordx2 v[160:161], v35, s[30:31] offset:400
	global_load_dwordx2 v[162:163], v35, s[30:31] offset:408
	global_load_dword v3, v48, s[24:25] offset:0
	global_load_dword v19, v48, s[26:27] offset:0
	global_load_dword v16, v48, s[24:25] offset:64
	global_load_dword v32, v48, s[26:27] offset:64
	global_load_dword v17, v48, s[24:25] offset:128
	global_load_dword v33, v48, s[26:27] offset:128
	global_load_dword v18, v48, s[24:25] offset:192
	global_load_dword v34, v48, s[26:27] offset:192
	global_load_dword v173, v[246:247], off offset:0
	global_load_dword v174, v[246:247], off offset:64
	global_load_dword v175, v[246:247], off offset:128
	global_load_dword v176, v[246:247], off offset:192
	global_load_dword v177, v165, s[28:29] offset:-4096
	global_load_dword v178, v165, s[28:29] offset:0
	global_load_dword v179, v166, s[28:29] offset:-4096
	global_load_dword v224, v166, s[28:29] offset:0
	global_load_dword v225, v167, s[28:29] offset:-4096
	global_load_dword v226, v167, s[28:29] offset:0
	global_load_dword v227, v168, s[28:29] offset:-4096
	global_load_dword v228, v168, s[28:29] offset:0
	global_load_dword v229, v169, s[28:29] offset:-4096
	global_load_dword v230, v169, s[28:29] offset:0
	global_load_dword v231, v170, s[28:29] offset:-4096
	global_load_dword v234, v170, s[28:29] offset:0
	global_load_dword v235, v171, s[28:29] offset:-4096
	global_load_dword v236, v171, s[28:29] offset:0
	global_load_dword v237, v172, s[28:29] offset:-4096
	global_load_dword v238, v172, s[28:29] offset:0
	global_load_dword v239, v165, s[28:29] offset:-4032
	global_load_dword v240, v165, s[28:29] offset:64
	global_load_dword v241, v166, s[28:29] offset:-4032
	global_load_dword v242, v166, s[28:29] offset:64
	global_load_dword v243, v167, s[28:29] offset:-4032
	global_load_dword v244, v167, s[28:29] offset:64
	global_load_dword v245, v168, s[28:29] offset:-4032
	global_load_dword v112, v168, s[28:29] offset:64
	global_load_dword v115, v169, s[28:29] offset:-4032
	global_load_dword v208, v169, s[28:29] offset:64
	global_load_dword v223, v170, s[28:29] offset:-4032
	global_load_dword v233, v170, s[28:29] offset:64
	global_load_dword v248, v171, s[28:29] offset:-4032
	global_load_dword v0, v171, s[28:29] offset:64
	global_load_dword v1, v172, s[28:29] offset:-4032
	global_load_dword v2, v172, s[28:29] offset:64
	s_waitcnt vmcnt(31)
	v_add_f32_e32 v173, 1.0, v173
	v_add_f32_e32 v174, 1.0, v174
	v_add_f32_e32 v175, 1.0, v175
	v_add_f32_e32 v176, 1.0, v176
	v_mul_f32_e32 v173, 0.5, v173
	v_mul_f32_e32 v174, 0.5, v174
	v_mul_f32_e32 v175, 0.5, v175
	v_mul_f32_e32 v176, 0.5, v176
	v_sub_f32_e32 v177, v177, v132
	v_mul_f32_e32 v177, v177, v133
	v_fma_f32 v177, v3, v177, v19
	v_mul_f32_e32 v64, v64, v173
	v_fmac_f32_e32 v64, 0x3fb504f3, v177
	global_load_dword v177, v165, s[28:29] offset:-3968
	global_store_dword v165, v64, s[28:29] offset:-4096
	s_waitcnt vmcnt(32)
	v_sub_f32_e32 v178, v178, v134
	v_mul_f32_e32 v178, v178, v135
	v_fma_f32 v178, v3, v178, v19
	v_mul_f32_e32 v65, v65, v173
	v_fmac_f32_e32 v65, 0x3fb504f3, v178
	global_load_dword v178, v165, s[28:29] offset:128
	global_store_dword v165, v65, s[28:29] offset:0
	s_waitcnt vmcnt(33)
	v_sub_f32_e32 v179, v179, v136
	v_mul_f32_e32 v179, v179, v137
	v_fma_f32 v179, v3, v179, v19
	v_mul_f32_e32 v66, v66, v173
	v_fmac_f32_e32 v66, 0x3fb504f3, v179
	global_load_dword v179, v166, s[28:29] offset:-3968
	global_store_dword v166, v66, s[28:29] offset:-4096
	s_waitcnt vmcnt(34)
	v_sub_f32_e32 v224, v224, v138
	v_mul_f32_e32 v224, v224, v139
	v_fma_f32 v224, v3, v224, v19
	v_mul_f32_e32 v67, v67, v173
	v_fmac_f32_e32 v67, 0x3fb504f3, v224
	global_load_dword v224, v166, s[28:29] offset:128
	global_store_dword v166, v67, s[28:29] offset:0
	s_waitcnt vmcnt(35)
	v_sub_f32_e32 v225, v225, v140
	v_mul_f32_e32 v225, v225, v141
	v_fma_f32 v225, v3, v225, v19
	v_mul_f32_e32 v80, v80, v173
	v_fmac_f32_e32 v80, 0x3fb504f3, v225
	global_load_dword v225, v167, s[28:29] offset:-3968
	global_store_dword v167, v80, s[28:29] offset:-4096
	s_waitcnt vmcnt(36)
	v_sub_f32_e32 v226, v226, v142
	v_mul_f32_e32 v226, v226, v143
	v_fma_f32 v226, v3, v226, v19
	v_mul_f32_e32 v81, v81, v173
	v_fmac_f32_e32 v81, 0x3fb504f3, v226
	global_load_dword v226, v167, s[28:29] offset:128
	global_store_dword v167, v81, s[28:29] offset:0
	s_waitcnt vmcnt(37)
	v_sub_f32_e32 v227, v227, v144
	v_mul_f32_e32 v227, v227, v145
	v_fma_f32 v227, v3, v227, v19
	v_mul_f32_e32 v82, v82, v173
	v_fmac_f32_e32 v82, 0x3fb504f3, v227
	global_load_dword v227, v168, s[28:29] offset:-3968
	global_store_dword v168, v82, s[28:29] offset:-4096
	s_waitcnt vmcnt(38)
	v_sub_f32_e32 v228, v228, v146
	v_mul_f32_e32 v228, v228, v147
	v_fma_f32 v228, v3, v228, v19
	v_mul_f32_e32 v83, v83, v173
	v_fmac_f32_e32 v83, 0x3fb504f3, v228
	global_load_dword v228, v168, s[28:29] offset:128
	global_store_dword v168, v83, s[28:29] offset:0
	s_waitcnt vmcnt(39)
	v_sub_f32_e32 v229, v229, v148
	v_mul_f32_e32 v229, v229, v149
	v_fma_f32 v229, v3, v229, v19
	v_mul_f32_e32 v96, v96, v173
	v_fmac_f32_e32 v96, 0x3fb504f3, v229
	global_load_dword v229, v169, s[28:29] offset:-3968
	global_store_dword v169, v96, s[28:29] offset:-4096
	s_waitcnt vmcnt(40)
	v_sub_f32_e32 v230, v230, v150
	v_mul_f32_e32 v230, v230, v151
	v_fma_f32 v230, v3, v230, v19
	v_mul_f32_e32 v97, v97, v173
	v_fmac_f32_e32 v97, 0x3fb504f3, v230
	global_load_dword v230, v169, s[28:29] offset:128
	global_store_dword v169, v97, s[28:29] offset:0
	s_waitcnt vmcnt(41)
	v_sub_f32_e32 v231, v231, v152
	v_mul_f32_e32 v231, v231, v153
	v_fma_f32 v231, v3, v231, v19
	v_mul_f32_e32 v98, v98, v173
	v_fmac_f32_e32 v98, 0x3fb504f3, v231
	global_load_dword v231, v170, s[28:29] offset:-3968
	global_store_dword v170, v98, s[28:29] offset:-4096
	s_waitcnt vmcnt(42)
	v_sub_f32_e32 v234, v234, v154
	v_mul_f32_e32 v234, v234, v155
	v_fma_f32 v234, v3, v234, v19
	v_mul_f32_e32 v99, v99, v173
	v_fmac_f32_e32 v99, 0x3fb504f3, v234
	global_load_dword v234, v170, s[28:29] offset:128
	global_store_dword v170, v99, s[28:29] offset:0
	s_waitcnt vmcnt(43)
	v_sub_f32_e32 v235, v235, v156
	v_mul_f32_e32 v235, v235, v157
	v_fma_f32 v235, v3, v235, v19
	v_mul_f32_e32 v116, v116, v173
	v_fmac_f32_e32 v116, 0x3fb504f3, v235
	global_load_dword v235, v171, s[28:29] offset:-3968
	global_store_dword v171, v116, s[28:29] offset:-4096
	s_waitcnt vmcnt(44)
	v_sub_f32_e32 v236, v236, v158
	v_mul_f32_e32 v236, v236, v159
	v_fma_f32 v236, v3, v236, v19
	v_mul_f32_e32 v117, v117, v173
	v_fmac_f32_e32 v117, 0x3fb504f3, v236
	global_load_dword v236, v171, s[28:29] offset:128
	global_store_dword v171, v117, s[28:29] offset:0
	s_waitcnt vmcnt(45)
	v_sub_f32_e32 v237, v237, v160
	v_mul_f32_e32 v237, v237, v161
	v_fma_f32 v237, v3, v237, v19
	v_mul_f32_e32 v118, v118, v173
	v_fmac_f32_e32 v118, 0x3fb504f3, v237
	global_load_dword v237, v172, s[28:29] offset:-3968
	global_store_dword v172, v118, s[28:29] offset:-4096
	s_waitcnt vmcnt(46)
	v_sub_f32_e32 v238, v238, v162
	v_mul_f32_e32 v238, v238, v163
	v_fma_f32 v238, v3, v238, v19
	v_mul_f32_e32 v119, v119, v173
	v_fmac_f32_e32 v119, 0x3fb504f3, v238
	global_load_dword v238, v172, s[28:29] offset:128
	global_store_dword v172, v119, s[28:29] offset:0
	s_waitcnt vmcnt(47)
	v_sub_f32_e32 v239, v239, v132
	v_mul_f32_e32 v239, v239, v133
	v_fma_f32 v239, v16, v239, v32
	v_mul_f32_e32 v68, v68, v174
	v_fmac_f32_e32 v68, 0x3fb504f3, v239
	global_load_dword v239, v165, s[28:29] offset:-3904
	global_store_dword v165, v68, s[28:29] offset:-4032
	s_waitcnt vmcnt(48)
	v_sub_f32_e32 v240, v240, v134
	v_mul_f32_e32 v240, v240, v135
	v_fma_f32 v240, v16, v240, v32
	v_mul_f32_e32 v69, v69, v174
	v_fmac_f32_e32 v69, 0x3fb504f3, v240
	global_load_dword v240, v165, s[28:29] offset:192
	global_store_dword v165, v69, s[28:29] offset:64
	s_waitcnt vmcnt(49)
	v_sub_f32_e32 v241, v241, v136
	v_mul_f32_e32 v241, v241, v137
	v_fma_f32 v241, v16, v241, v32
	v_mul_f32_e32 v70, v70, v174
	v_fmac_f32_e32 v70, 0x3fb504f3, v241
	global_load_dword v241, v166, s[28:29] offset:-3904
	global_store_dword v166, v70, s[28:29] offset:-4032
	s_waitcnt vmcnt(50)
	v_sub_f32_e32 v242, v242, v138
	v_mul_f32_e32 v242, v242, v139
	v_fma_f32 v242, v16, v242, v32
	v_mul_f32_e32 v71, v71, v174
	v_fmac_f32_e32 v71, 0x3fb504f3, v242
	global_load_dword v242, v166, s[28:29] offset:192
	global_store_dword v166, v71, s[28:29] offset:64
	s_waitcnt vmcnt(51)
	v_sub_f32_e32 v243, v243, v140
	v_mul_f32_e32 v243, v243, v141
	v_fma_f32 v243, v16, v243, v32
	v_mul_f32_e32 v84, v84, v174
	v_fmac_f32_e32 v84, 0x3fb504f3, v243
	global_load_dword v243, v167, s[28:29] offset:-3904
	global_store_dword v167, v84, s[28:29] offset:-4032
	s_waitcnt vmcnt(52)
	v_sub_f32_e32 v244, v244, v142
	v_mul_f32_e32 v244, v244, v143
	v_fma_f32 v244, v16, v244, v32
	v_mul_f32_e32 v85, v85, v174
	v_fmac_f32_e32 v85, 0x3fb504f3, v244
	global_load_dword v244, v167, s[28:29] offset:192
	global_store_dword v167, v85, s[28:29] offset:64
	s_waitcnt vmcnt(53)
	v_sub_f32_e32 v245, v245, v144
	v_mul_f32_e32 v245, v245, v145
	v_fma_f32 v245, v16, v245, v32
	v_mul_f32_e32 v86, v86, v174
	v_fmac_f32_e32 v86, 0x3fb504f3, v245
	global_load_dword v245, v168, s[28:29] offset:-3904
	global_store_dword v168, v86, s[28:29] offset:-4032
	s_waitcnt vmcnt(54)
	v_sub_f32_e32 v112, v112, v146
	v_mul_f32_e32 v112, v112, v147
	v_fma_f32 v112, v16, v112, v32
	v_mul_f32_e32 v87, v87, v174
	v_fmac_f32_e32 v87, 0x3fb504f3, v112
	global_load_dword v112, v168, s[28:29] offset:192
	global_store_dword v168, v87, s[28:29] offset:64
	s_waitcnt vmcnt(55)
	v_sub_f32_e32 v115, v115, v148
	v_mul_f32_e32 v115, v115, v149
	v_fma_f32 v115, v16, v115, v32
	v_mul_f32_e32 v100, v100, v174
	v_fmac_f32_e32 v100, 0x3fb504f3, v115
	global_load_dword v115, v169, s[28:29] offset:-3904
	global_store_dword v169, v100, s[28:29] offset:-4032
	s_waitcnt vmcnt(56)
	v_sub_f32_e32 v208, v208, v150
	v_mul_f32_e32 v208, v208, v151
	v_fma_f32 v208, v16, v208, v32
	v_mul_f32_e32 v101, v101, v174
	v_fmac_f32_e32 v101, 0x3fb504f3, v208
	global_load_dword v208, v169, s[28:29] offset:192
	global_store_dword v169, v101, s[28:29] offset:64
	s_waitcnt vmcnt(57)
	v_sub_f32_e32 v223, v223, v152
	v_mul_f32_e32 v223, v223, v153
	v_fma_f32 v223, v16, v223, v32
	v_mul_f32_e32 v102, v102, v174
	v_fmac_f32_e32 v102, 0x3fb504f3, v223
	global_load_dword v223, v170, s[28:29] offset:-3904
	global_store_dword v170, v102, s[28:29] offset:-4032
	s_waitcnt vmcnt(58)
	v_sub_f32_e32 v233, v233, v154
	v_mul_f32_e32 v233, v233, v155
	v_fma_f32 v233, v16, v233, v32
	v_mul_f32_e32 v103, v103, v174
	v_fmac_f32_e32 v103, 0x3fb504f3, v233
	global_load_dword v233, v170, s[28:29] offset:192
	global_store_dword v170, v103, s[28:29] offset:64
	s_waitcnt vmcnt(59)
	v_sub_f32_e32 v248, v248, v156
	v_mul_f32_e32 v248, v248, v157
	v_fma_f32 v248, v16, v248, v32
	v_mul_f32_e32 v120, v120, v174
	v_fmac_f32_e32 v120, 0x3fb504f3, v248
	global_load_dword v248, v171, s[28:29] offset:-3904
	global_store_dword v171, v120, s[28:29] offset:-4032
	s_waitcnt vmcnt(60)
	v_sub_f32_e32 v0, v0, v158
	v_mul_f32_e32 v0, v0, v159
	v_fma_f32 v0, v16, v0, v32
	v_mul_f32_e32 v121, v121, v174
	v_fmac_f32_e32 v121, 0x3fb504f3, v0
	global_load_dword v0, v171, s[28:29] offset:192
	global_store_dword v171, v121, s[28:29] offset:64
	s_waitcnt vmcnt(61)
	v_sub_f32_e32 v1, v1, v160
	v_mul_f32_e32 v1, v1, v161
	v_fma_f32 v1, v16, v1, v32
	v_mul_f32_e32 v122, v122, v174
	v_fmac_f32_e32 v122, 0x3fb504f3, v1
	global_load_dword v1, v172, s[28:29] offset:-3904
	global_store_dword v172, v122, s[28:29] offset:-4032
	s_waitcnt vmcnt(62)
	v_sub_f32_e32 v2, v2, v162
	v_mul_f32_e32 v2, v2, v163
	v_fma_f32 v2, v16, v2, v32
	v_mul_f32_e32 v123, v123, v174
	v_fmac_f32_e32 v123, 0x3fb504f3, v2
	global_load_dword v2, v172, s[28:29] offset:192
	global_store_dword v172, v123, s[28:29] offset:64
	s_waitcnt vmcnt(63)
	v_sub_f32_e32 v177, v177, v132
	v_mul_f32_e32 v177, v177, v133
	v_fma_f32 v177, v17, v177, v33
	v_mul_f32_e32 v72, v72, v175
	v_fmac_f32_e32 v72, 0x3fb504f3, v177
	global_store_dword v165, v72, s[28:29] offset:-3968
	s_waitcnt vmcnt(62)
	v_sub_f32_e32 v178, v178, v134
	v_mul_f32_e32 v178, v178, v135
	v_fma_f32 v178, v17, v178, v33
	v_mul_f32_e32 v73, v73, v175
	v_fmac_f32_e32 v73, 0x3fb504f3, v178
	global_store_dword v165, v73, s[28:29] offset:128
	s_waitcnt vmcnt(61)
	v_sub_f32_e32 v179, v179, v136
	v_mul_f32_e32 v179, v179, v137
	v_fma_f32 v179, v17, v179, v33
	v_mul_f32_e32 v74, v74, v175
	v_fmac_f32_e32 v74, 0x3fb504f3, v179
	global_store_dword v166, v74, s[28:29] offset:-3968
	s_waitcnt vmcnt(60)
	v_sub_f32_e32 v224, v224, v138
	v_mul_f32_e32 v224, v224, v139
	v_fma_f32 v224, v17, v224, v33
	v_mul_f32_e32 v75, v75, v175
	v_fmac_f32_e32 v75, 0x3fb504f3, v224
	global_store_dword v166, v75, s[28:29] offset:128
	s_waitcnt vmcnt(59)
	v_sub_f32_e32 v225, v225, v140
	v_mul_f32_e32 v225, v225, v141
	v_fma_f32 v225, v17, v225, v33
	v_mul_f32_e32 v88, v88, v175
	v_fmac_f32_e32 v88, 0x3fb504f3, v225
	global_store_dword v167, v88, s[28:29] offset:-3968
	s_waitcnt vmcnt(58)
	v_sub_f32_e32 v226, v226, v142
	v_mul_f32_e32 v226, v226, v143
	v_fma_f32 v226, v17, v226, v33
	v_mul_f32_e32 v89, v89, v175
	v_fmac_f32_e32 v89, 0x3fb504f3, v226
	global_store_dword v167, v89, s[28:29] offset:128
	s_waitcnt vmcnt(57)
	v_sub_f32_e32 v227, v227, v144
	v_mul_f32_e32 v227, v227, v145
	v_fma_f32 v227, v17, v227, v33
	v_mul_f32_e32 v90, v90, v175
	v_fmac_f32_e32 v90, 0x3fb504f3, v227
	global_store_dword v168, v90, s[28:29] offset:-3968
	s_waitcnt vmcnt(56)
	v_sub_f32_e32 v228, v228, v146
	v_mul_f32_e32 v228, v228, v147
	v_fma_f32 v228, v17, v228, v33
	v_mul_f32_e32 v91, v91, v175
	v_fmac_f32_e32 v91, 0x3fb504f3, v228
	global_store_dword v168, v91, s[28:29] offset:128
	s_waitcnt vmcnt(55)
	v_sub_f32_e32 v229, v229, v148
	v_mul_f32_e32 v229, v229, v149
	v_fma_f32 v229, v17, v229, v33
	v_mul_f32_e32 v104, v104, v175
	v_fmac_f32_e32 v104, 0x3fb504f3, v229
	global_store_dword v169, v104, s[28:29] offset:-3968
	s_waitcnt vmcnt(54)
	v_sub_f32_e32 v230, v230, v150
	v_mul_f32_e32 v230, v230, v151
	v_fma_f32 v230, v17, v230, v33
	v_mul_f32_e32 v105, v105, v175
	v_fmac_f32_e32 v105, 0x3fb504f3, v230
	global_store_dword v169, v105, s[28:29] offset:128
	s_waitcnt vmcnt(53)
	v_sub_f32_e32 v231, v231, v152
	v_mul_f32_e32 v231, v231, v153
	v_fma_f32 v231, v17, v231, v33
	v_mul_f32_e32 v106, v106, v175
	v_fmac_f32_e32 v106, 0x3fb504f3, v231
	global_store_dword v170, v106, s[28:29] offset:-3968
	s_waitcnt vmcnt(52)
	v_sub_f32_e32 v234, v234, v154
	v_mul_f32_e32 v234, v234, v155
	v_fma_f32 v234, v17, v234, v33
	v_mul_f32_e32 v107, v107, v175
	v_fmac_f32_e32 v107, 0x3fb504f3, v234
	global_store_dword v170, v107, s[28:29] offset:128
	s_waitcnt vmcnt(51)
	v_sub_f32_e32 v235, v235, v156
	v_mul_f32_e32 v235, v235, v157
	v_fma_f32 v235, v17, v235, v33
	v_mul_f32_e32 v124, v124, v175
	v_fmac_f32_e32 v124, 0x3fb504f3, v235
	global_store_dword v171, v124, s[28:29] offset:-3968
	s_waitcnt vmcnt(50)
	v_sub_f32_e32 v236, v236, v158
	v_mul_f32_e32 v236, v236, v159
	v_fma_f32 v236, v17, v236, v33
	v_mul_f32_e32 v125, v125, v175
	v_fmac_f32_e32 v125, 0x3fb504f3, v236
	global_store_dword v171, v125, s[28:29] offset:128
	s_waitcnt vmcnt(49)
	v_sub_f32_e32 v237, v237, v160
	v_mul_f32_e32 v237, v237, v161
	v_fma_f32 v237, v17, v237, v33
	v_mul_f32_e32 v126, v126, v175
	v_fmac_f32_e32 v126, 0x3fb504f3, v237
	global_store_dword v172, v126, s[28:29] offset:-3968
	s_waitcnt vmcnt(48)
	v_sub_f32_e32 v238, v238, v162
	v_mul_f32_e32 v238, v238, v163
	v_fma_f32 v238, v17, v238, v33
	v_mul_f32_e32 v127, v127, v175
	v_fmac_f32_e32 v127, 0x3fb504f3, v238
	global_store_dword v172, v127, s[28:29] offset:128
	s_waitcnt vmcnt(47)
	v_sub_f32_e32 v239, v239, v132
	v_mul_f32_e32 v239, v239, v133
	v_fma_f32 v239, v18, v239, v34
	v_mul_f32_e32 v76, v76, v176
	v_fmac_f32_e32 v76, 0x3fb504f3, v239
	global_store_dword v165, v76, s[28:29] offset:-3904
	s_waitcnt vmcnt(46)
	v_sub_f32_e32 v240, v240, v134
	v_mul_f32_e32 v240, v240, v135
	v_fma_f32 v240, v18, v240, v34
	v_mul_f32_e32 v77, v77, v176
	v_fmac_f32_e32 v77, 0x3fb504f3, v240
	global_store_dword v165, v77, s[28:29] offset:192
	s_waitcnt vmcnt(45)
	v_sub_f32_e32 v241, v241, v136
	v_mul_f32_e32 v241, v241, v137
	v_fma_f32 v241, v18, v241, v34
	v_mul_f32_e32 v78, v78, v176
	v_fmac_f32_e32 v78, 0x3fb504f3, v241
	global_store_dword v166, v78, s[28:29] offset:-3904
	s_waitcnt vmcnt(44)
	v_sub_f32_e32 v242, v242, v138
	v_mul_f32_e32 v242, v242, v139
	v_fma_f32 v242, v18, v242, v34
	v_mul_f32_e32 v79, v79, v176
	v_fmac_f32_e32 v79, 0x3fb504f3, v242
	global_store_dword v166, v79, s[28:29] offset:192
	s_waitcnt vmcnt(43)
	v_sub_f32_e32 v243, v243, v140
	v_mul_f32_e32 v243, v243, v141
	v_fma_f32 v243, v18, v243, v34
	v_mul_f32_e32 v92, v92, v176
	v_fmac_f32_e32 v92, 0x3fb504f3, v243
	global_store_dword v167, v92, s[28:29] offset:-3904
	s_waitcnt vmcnt(42)
	v_sub_f32_e32 v244, v244, v142
	v_mul_f32_e32 v244, v244, v143
	v_fma_f32 v244, v18, v244, v34
	v_mul_f32_e32 v93, v93, v176
	v_fmac_f32_e32 v93, 0x3fb504f3, v244
	global_store_dword v167, v93, s[28:29] offset:192
	s_waitcnt vmcnt(41)
	v_sub_f32_e32 v245, v245, v144
	v_mul_f32_e32 v245, v245, v145
	v_fma_f32 v245, v18, v245, v34
	v_mul_f32_e32 v94, v94, v176
	v_fmac_f32_e32 v94, 0x3fb504f3, v245
	global_store_dword v168, v94, s[28:29] offset:-3904
	s_waitcnt vmcnt(40)
	v_sub_f32_e32 v112, v112, v146
	v_mul_f32_e32 v112, v112, v147
	v_fma_f32 v112, v18, v112, v34
	v_mul_f32_e32 v95, v95, v176
	v_fmac_f32_e32 v95, 0x3fb504f3, v112
	global_store_dword v168, v95, s[28:29] offset:192
	s_waitcnt vmcnt(39)
	v_sub_f32_e32 v115, v115, v148
	v_mul_f32_e32 v115, v115, v149
	v_fma_f32 v115, v18, v115, v34
	v_mul_f32_e32 v108, v108, v176
	v_fmac_f32_e32 v108, 0x3fb504f3, v115
	global_store_dword v169, v108, s[28:29] offset:-3904
	s_waitcnt vmcnt(38)
	v_sub_f32_e32 v208, v208, v150
	v_mul_f32_e32 v208, v208, v151
	v_fma_f32 v208, v18, v208, v34
	v_mul_f32_e32 v109, v109, v176
	v_fmac_f32_e32 v109, 0x3fb504f3, v208
	global_store_dword v169, v109, s[28:29] offset:192
	s_waitcnt vmcnt(37)
	v_sub_f32_e32 v223, v223, v152
	v_mul_f32_e32 v223, v223, v153
	v_fma_f32 v223, v18, v223, v34
	v_mul_f32_e32 v110, v110, v176
	v_fmac_f32_e32 v110, 0x3fb504f3, v223
	global_store_dword v170, v110, s[28:29] offset:-3904
	s_waitcnt vmcnt(36)
	v_sub_f32_e32 v233, v233, v154
	v_mul_f32_e32 v233, v233, v155
	v_fma_f32 v233, v18, v233, v34
	v_mul_f32_e32 v111, v111, v176
	v_fmac_f32_e32 v111, 0x3fb504f3, v233
	global_store_dword v170, v111, s[28:29] offset:192
	s_waitcnt vmcnt(35)
	v_sub_f32_e32 v248, v248, v156
	v_mul_f32_e32 v248, v248, v157
	v_fma_f32 v248, v18, v248, v34
	v_mul_f32_e32 v128, v128, v176
	v_fmac_f32_e32 v128, 0x3fb504f3, v248
	global_store_dword v171, v128, s[28:29] offset:-3904
	s_waitcnt vmcnt(34)
	v_sub_f32_e32 v0, v0, v158
	v_mul_f32_e32 v0, v0, v159
	v_fma_f32 v0, v18, v0, v34
	v_mul_f32_e32 v129, v129, v176
	v_fmac_f32_e32 v129, 0x3fb504f3, v0
	global_store_dword v171, v129, s[28:29] offset:192
	s_waitcnt vmcnt(33)
	v_sub_f32_e32 v1, v1, v160
	v_mul_f32_e32 v1, v1, v161
	v_fma_f32 v1, v18, v1, v34
	v_mul_f32_e32 v130, v130, v176
	v_fmac_f32_e32 v130, 0x3fb504f3, v1
	global_store_dword v172, v130, s[28:29] offset:-3904
	s_waitcnt vmcnt(32)
	v_sub_f32_e32 v2, v2, v162
	v_mul_f32_e32 v2, v2, v163
	v_fma_f32 v2, v18, v2, v34
	v_mul_f32_e32 v131, v131, v176
	v_fmac_f32_e32 v131, 0x3fb504f3, v2
	global_store_dword v172, v131, s[28:29] offset:192
	s_add_i32 s11, s11, s59
	s_cmpk_gt_i32 s11, 0x3ff
	s_cbranch_scc0 .LBB0_649
	v_mov_b32_e32 v113, 0
	v_mov_b32_e32 v114, 0x3f317218
